# hoist the 8 serialized rs[row] loads of the 4 rs-scaled GEMM epilogues to tile start (no vmcnt(0) chain in epilogue)
# speedup vs baseline: 1.0039x; 1.0039x over previous
.LBB0_175:
	s_ashr_i32 s43, s42, 31
	s_lshl_b64 s[10:11], s[42:43], 20
	s_add_u32 s44, s51, s10
	s_addc_u32 s45, s52, s11
	s_and_b64 s[10:11], s[38:39], exec
	s_cselect_b32 s3, s45, s27
	s_cselect_b32 s10, s44, s26
	s_ashr_i32 s29, s28, 31
	s_lshl_b64 s[36:37], s[28:29], 20
	s_add_u32 s46, s7, s36
	s_addc_u32 s47, s53, s37
	s_and_b64 s[36:37], s[38:39], exec
	s_cselect_b32 s11, s47, s35
	s_cselect_b32 s21, s46, s34
	s_add_u32 s26, s26, 0x80080
	s_addc_u32 s27, s27, 0
	s_add_u32 s22, s34, 0x100
	v_mov_b32_e32 v4, 0
	s_addc_u32 s29, s35, 0
	s_mov_b32 s33, -2
	v_mov_b32_e32 v5, v4
	v_mov_b32_e32 v6, v4
	v_mov_b32_e32 v7, v4
	v_mov_b32_e32 v8, v4
	v_mov_b32_e32 v9, v4
	v_mov_b32_e32 v10, v4
	v_mov_b32_e32 v11, v4
	v_mov_b32_e32 v20, v4
	v_mov_b32_e32 v21, v4
	v_mov_b32_e32 v22, v4
	v_mov_b32_e32 v23, v4
	v_mov_b32_e32 v24, v4
	v_mov_b32_e32 v25, v4
	v_mov_b32_e32 v26, v4
	v_mov_b32_e32 v27, v4
	v_mov_b32_e32 v36, v4
	v_mov_b32_e32 v37, v4
	v_mov_b32_e32 v38, v4
	v_mov_b32_e32 v39, v4
	v_mov_b32_e32 v40, v4
	v_mov_b32_e32 v41, v4
	v_mov_b32_e32 v42, v4
	v_mov_b32_e32 v43, v4
	v_mov_b32_e32 v52, v4
	v_mov_b32_e32 v53, v4
	v_mov_b32_e32 v54, v4
	v_mov_b32_e32 v55, v4
	v_mov_b32_e32 v56, v4
	v_mov_b32_e32 v57, v4
	v_mov_b32_e32 v58, v4
	v_mov_b32_e32 v59, v4
	v_mov_b32_e32 v12, v4
	v_mov_b32_e32 v13, v4
	v_mov_b32_e32 v14, v4
	v_mov_b32_e32 v15, v4
	v_mov_b32_e32 v16, v4
	v_mov_b32_e32 v17, v4
	v_mov_b32_e32 v18, v4
	v_mov_b32_e32 v19, v4
	v_mov_b32_e32 v28, v4
	v_mov_b32_e32 v29, v4
	v_mov_b32_e32 v30, v4
	v_mov_b32_e32 v31, v4
	v_mov_b32_e32 v32, v4
	v_mov_b32_e32 v33, v4
	v_mov_b32_e32 v34, v4
	v_mov_b32_e32 v35, v4
	v_mov_b32_e32 v44, v4
	v_mov_b32_e32 v45, v4
	v_mov_b32_e32 v46, v4
	v_mov_b32_e32 v47, v4
	v_mov_b32_e32 v48, v4
	v_mov_b32_e32 v49, v4
	v_mov_b32_e32 v50, v4
	v_mov_b32_e32 v51, v4
	v_mov_b32_e32 v60, v4
	v_mov_b32_e32 v61, v4
	v_mov_b32_e32 v62, v4
	v_mov_b32_e32 v63, v4
	v_mov_b32_e32 v64, v4
	v_mov_b32_e32 v65, v4
	v_mov_b32_e32 v66, v4
	v_mov_b32_e32 v67, v4
	v_mov_b32_e32 v68, v4
	v_mov_b32_e32 v69, v4
	v_mov_b32_e32 v70, v4
	v_mov_b32_e32 v71, v4
	v_mov_b32_e32 v72, v4
	v_mov_b32_e32 v73, v4
	v_mov_b32_e32 v74, v4
	v_mov_b32_e32 v75, v4
	v_mov_b32_e32 v84, v4
	v_mov_b32_e32 v85, v4
	v_mov_b32_e32 v86, v4
	v_mov_b32_e32 v87, v4
	v_mov_b32_e32 v88, v4
	v_mov_b32_e32 v89, v4
	v_mov_b32_e32 v90, v4
	v_mov_b32_e32 v91, v4
	v_mov_b32_e32 v100, v4
	v_mov_b32_e32 v101, v4
	v_mov_b32_e32 v102, v4
	v_mov_b32_e32 v103, v4
	v_mov_b32_e32 v104, v4
	v_mov_b32_e32 v105, v4
	v_mov_b32_e32 v106, v4
	v_mov_b32_e32 v107, v4
	v_mov_b32_e32 v116, v4
	v_mov_b32_e32 v117, v4
	v_mov_b32_e32 v118, v4
	v_mov_b32_e32 v119, v4
	v_mov_b32_e32 v120, v4
	v_mov_b32_e32 v121, v4
	v_mov_b32_e32 v122, v4
	v_mov_b32_e32 v123, v4
	v_mov_b32_e32 v76, v4
	v_mov_b32_e32 v77, v4
	v_mov_b32_e32 v78, v4
	v_mov_b32_e32 v79, v4
	v_mov_b32_e32 v80, v4
	v_mov_b32_e32 v81, v4
	v_mov_b32_e32 v82, v4
	v_mov_b32_e32 v83, v4
	v_mov_b32_e32 v92, v4
	v_mov_b32_e32 v93, v4
	v_mov_b32_e32 v94, v4
	v_mov_b32_e32 v95, v4
	v_mov_b32_e32 v96, v4
	v_mov_b32_e32 v97, v4
	v_mov_b32_e32 v98, v4
	v_mov_b32_e32 v99, v4
	v_mov_b32_e32 v108, v4
	v_mov_b32_e32 v109, v4
	v_mov_b32_e32 v110, v4
	v_mov_b32_e32 v111, v4
	v_mov_b32_e32 v112, v4
	v_mov_b32_e32 v113, v4
	v_mov_b32_e32 v114, v4
	v_mov_b32_e32 v115, v4
	v_mov_b32_e32 v124, v4
	v_mov_b32_e32 v125, v4
	v_mov_b32_e32 v126, v4
	v_mov_b32_e32 v127, v4
	v_mov_b32_e32 v128, v4
	v_mov_b32_e32 v129, v4
	v_mov_b32_e32 v130, v4
	v_mov_b32_e32 v131, v4
	v_lshl_add_u32 v148, s2, 8, v150
	v_ashrrev_i32_e32 v149, 31, v148
	v_lshl_add_u64 v[144:145], v[148:149], 2, s[40:41]
	global_load_dword v244, v[144:145], off
	global_load_dword v245, v[144:145], off offset:64
	global_load_dword v246, v[144:145], off offset:128
	global_load_dword v247, v[144:145], off offset:192
	global_load_dword v248, v[144:145], off offset:512
	global_load_dword v249, v[144:145], off offset:576
	global_load_dword v250, v[144:145], off offset:640
	global_load_dword v251, v[144:145], off offset:704

.LBB0_179:
	v_lshl_add_u32 v148, s2, 8, v150
	v_ashrrev_i32_e32 v149, 31, v148
	v_lshl_add_u64 v[144:145], v[148:149], 2, s[40:41]
	s_nop 0
	v_lshl_or_b32 v142, s1, 8, v152
	v_ashrrev_i32_e32 v143, 31, v142
	v_lshlrev_b64 v[146:147], 12, v[148:149]
	v_lshl_add_u64 v[156:157], s[8:9], 0, v[146:147]
	v_lshlrev_b64 v[146:147], 1, v[142:143]
	v_lshl_add_u64 v[142:143], v[156:157], 0, v[146:147]
	s_mov_b64 s[0:1], 0x80000
	s_mov_b64 s[2:3], -1
	s_movk_i32 s33, 0x7ff
	v_mov_b32_e32 v154, v244
	v_pk_mul_f32 v[130:131], v[130:131], v[154:155] op_sel_hi:[1,0]
	v_pk_mul_f32 v[128:129], v[128:129], v[154:155] op_sel_hi:[1,0]
	v_pk_mul_f32 v[156:157], v[126:127], v[154:155] op_sel_hi:[1,0]
	v_pk_mul_f32 v[126:127], v[124:125], v[154:155] op_sel_hi:[1,0]
	v_cvt_pk_bf16_f32 v124, v128, v129
	v_cvt_pk_bf16_f32 v125, v130, v131
	v_pk_mul_f32 v[120:121], v[120:121], v[154:155] op_sel_hi:[1,0]
	v_cvt_pk_bf16_f32 v126, v126, v127
	v_cvt_pk_bf16_f32 v127, v156, v157
	global_store_dwordx4 v[142:143], v[124:127], off
	v_pk_mul_f32 v[122:123], v[122:123], v[154:155] op_sel_hi:[1,0]
	s_nop 0
	v_pk_mul_f32 v[124:125], v[118:119], v[154:155] op_sel_hi:[1,0]
	v_pk_mul_f32 v[118:119], v[116:117], v[154:155] op_sel_hi:[1,0]
	v_cvt_pk_bf16_f32 v116, v120, v121
	v_cvt_pk_bf16_f32 v117, v122, v123
	s_nop 0
	v_cvt_pk_bf16_f32 v118, v118, v119
	v_cvt_pk_bf16_f32 v119, v124, v125
	global_store_dwordx4 v[142:143], v[116:119], off offset:256
	s_nop 1
	v_or_b32_e32 v116, 16, v148
	v_ashrrev_i32_e32 v117, 31, v116
	v_lshl_add_u64 v[118:119], v[116:117], 2, s[40:41]
	s_nop 0
	v_lshlrev_b64 v[116:117], 12, v[116:117]
	v_lshl_add_u64 v[116:117], s[8:9], 0, v[116:117]
	v_lshl_add_u64 v[116:117], v[116:117], 0, v[146:147]
	v_mov_b32_e32 v118, v245
	v_pk_mul_f32 v[114:115], v[114:115], v[118:119] op_sel_hi:[1,0]
	v_pk_mul_f32 v[112:113], v[112:113], v[118:119] op_sel_hi:[1,0]
	v_pk_mul_f32 v[120:121], v[110:111], v[118:119] op_sel_hi:[1,0]
	v_pk_mul_f32 v[110:111], v[108:109], v[118:119] op_sel_hi:[1,0]
	v_cvt_pk_bf16_f32 v108, v112, v113
	v_cvt_pk_bf16_f32 v109, v114, v115
	v_pk_mul_f32 v[104:105], v[104:105], v[118:119] op_sel_hi:[1,0]
	v_cvt_pk_bf16_f32 v110, v110, v111
	v_cvt_pk_bf16_f32 v111, v120, v121
	global_store_dwordx4 v[116:117], v[108:111], off
	v_pk_mul_f32 v[106:107], v[106:107], v[118:119] op_sel_hi:[1,0]
	s_nop 0
	v_pk_mul_f32 v[108:109], v[102:103], v[118:119] op_sel_hi:[1,0]
	v_pk_mul_f32 v[102:103], v[100:101], v[118:119] op_sel_hi:[1,0]
	v_cvt_pk_bf16_f32 v100, v104, v105
	v_cvt_pk_bf16_f32 v101, v106, v107
	s_nop 0
	v_cvt_pk_bf16_f32 v102, v102, v103
	v_cvt_pk_bf16_f32 v103, v108, v109
	global_store_dwordx4 v[116:117], v[100:103], off offset:256
	s_nop 1
	v_or_b32_e32 v100, 32, v148
	v_ashrrev_i32_e32 v101, 31, v100
	v_lshl_add_u64 v[102:103], v[100:101], 2, s[40:41]
	s_nop 0
	v_lshlrev_b64 v[100:101], 12, v[100:101]
	v_lshl_add_u64 v[100:101], s[8:9], 0, v[100:101]
	v_lshl_add_u64 v[100:101], v[100:101], 0, v[146:147]
	v_mov_b32_e32 v102, v246
	v_pk_mul_f32 v[98:99], v[98:99], v[102:103] op_sel_hi:[1,0]
	v_pk_mul_f32 v[96:97], v[96:97], v[102:103] op_sel_hi:[1,0]
	v_pk_mul_f32 v[104:105], v[94:95], v[102:103] op_sel_hi:[1,0]
	v_pk_mul_f32 v[94:95], v[92:93], v[102:103] op_sel_hi:[1,0]
	v_cvt_pk_bf16_f32 v92, v96, v97
	v_cvt_pk_bf16_f32 v93, v98, v99
	v_pk_mul_f32 v[88:89], v[88:89], v[102:103] op_sel_hi:[1,0]
	v_cvt_pk_bf16_f32 v94, v94, v95
	v_cvt_pk_bf16_f32 v95, v104, v105
	global_store_dwordx4 v[100:101], v[92:95], off
	v_pk_mul_f32 v[90:91], v[90:91], v[102:103] op_sel_hi:[1,0]
	s_nop 0
	v_pk_mul_f32 v[92:93], v[86:87], v[102:103] op_sel_hi:[1,0]
	v_pk_mul_f32 v[86:87], v[84:85], v[102:103] op_sel_hi:[1,0]
	v_cvt_pk_bf16_f32 v84, v88, v89
	v_cvt_pk_bf16_f32 v85, v90, v91
	s_nop 0
	v_cvt_pk_bf16_f32 v86, v86, v87
	v_cvt_pk_bf16_f32 v87, v92, v93
	global_store_dwordx4 v[100:101], v[84:87], off offset:256
	s_nop 1
	v_or_b32_e32 v84, 48, v148
	v_ashrrev_i32_e32 v85, 31, v84
	v_lshl_add_u64 v[86:87], v[84:85], 2, s[40:41]
	s_nop 0
	v_lshlrev_b64 v[84:85], 12, v[84:85]
	v_lshl_add_u64 v[84:85], s[8:9], 0, v[84:85]
	v_lshl_add_u64 v[84:85], v[84:85], 0, v[146:147]
	v_mov_b32_e32 v86, v247
	v_pk_mul_f32 v[82:83], v[82:83], v[86:87] op_sel_hi:[1,0]
	v_pk_mul_f32 v[80:81], v[80:81], v[86:87] op_sel_hi:[1,0]
	v_pk_mul_f32 v[88:89], v[78:79], v[86:87] op_sel_hi:[1,0]
	v_pk_mul_f32 v[78:79], v[76:77], v[86:87] op_sel_hi:[1,0]
	v_cvt_pk_bf16_f32 v76, v80, v81
	v_cvt_pk_bf16_f32 v77, v82, v83
	v_pk_mul_f32 v[74:75], v[74:75], v[86:87] op_sel_hi:[1,0]
	v_cvt_pk_bf16_f32 v78, v78, v79
	v_cvt_pk_bf16_f32 v79, v88, v89
	global_store_dwordx4 v[84:85], v[76:79], off
	v_pk_mul_f32 v[72:73], v[72:73], v[86:87] op_sel_hi:[1,0]
	s_nop 0
	v_pk_mul_f32 v[76:77], v[70:71], v[86:87] op_sel_hi:[1,0]
	v_pk_mul_f32 v[70:71], v[68:69], v[86:87] op_sel_hi:[1,0]
	v_cvt_pk_bf16_f32 v68, v72, v73
	v_cvt_pk_bf16_f32 v69, v74, v75
	s_nop 0
	v_cvt_pk_bf16_f32 v70, v70, v71
	v_cvt_pk_bf16_f32 v71, v76, v77
	global_store_dwordx4 v[84:85], v[68:71], off offset:256
	s_nop 0
	s_nop 0
	v_mov_b32_e32 v68, v248
	v_pk_mul_f32 v[64:65], v[64:65], v[68:69] op_sel_hi:[1,0]
	v_lshl_add_u64 v[70:71], v[142:143], 0, s[0:1]
	s_mov_b32 s0, 0x80000
	v_pk_mul_f32 v[72:73], v[62:63], v[68:69] op_sel_hi:[1,0]
	v_pk_mul_f32 v[62:63], v[60:61], v[68:69] op_sel_hi:[1,0]
	v_cvt_pk_bf16_f32 v60, v64, v65
	v_add_co_u32_e32 v64, vcc, s0, v142
	v_pk_mul_f32 v[66:67], v[66:67], v[68:69] op_sel_hi:[1,0]
	s_nop 0
	v_addc_co_u32_e32 v65, vcc, 0, v143, vcc
	v_cvt_pk_bf16_f32 v61, v66, v67
	v_cvt_pk_bf16_f32 v62, v62, v63
	v_cvt_pk_bf16_f32 v63, v72, v73
	global_store_dwordx4 v[64:65], v[60:63], off
	v_pk_mul_f32 v[58:59], v[58:59], v[68:69] op_sel_hi:[1,0]
	v_pk_mul_f32 v[56:57], v[56:57], v[68:69] op_sel_hi:[1,0]
	v_pk_mul_f32 v[60:61], v[54:55], v[68:69] op_sel_hi:[1,0]
	v_pk_mul_f32 v[54:55], v[52:53], v[68:69] op_sel_hi:[1,0]
	v_cvt_pk_bf16_f32 v52, v56, v57
	v_cvt_pk_bf16_f32 v53, v58, v59
	s_mov_b64 s[0:1], 0x90000
	v_cvt_pk_bf16_f32 v54, v54, v55
	v_cvt_pk_bf16_f32 v55, v60, v61
	global_store_dwordx4 v[70:71], v[52:55], off offset:256
	s_nop 0
	s_nop 0
	v_mov_b32_e32 v52, v249
	v_pk_mul_f32 v[48:49], v[48:49], v[52:53] op_sel_hi:[1,0]
	v_lshl_add_u64 v[54:55], v[142:143], 0, s[0:1]
	s_mov_b32 s0, 0x90000
	v_pk_mul_f32 v[56:57], v[46:47], v[52:53] op_sel_hi:[1,0]
	v_pk_mul_f32 v[46:47], v[44:45], v[52:53] op_sel_hi:[1,0]
	v_cvt_pk_bf16_f32 v44, v48, v49
	v_add_co_u32_e32 v48, vcc, s0, v142
	v_pk_mul_f32 v[50:51], v[50:51], v[52:53] op_sel_hi:[1,0]
	s_nop 0
	v_addc_co_u32_e32 v49, vcc, 0, v143, vcc
	v_cvt_pk_bf16_f32 v45, v50, v51
	v_cvt_pk_bf16_f32 v46, v46, v47
	v_cvt_pk_bf16_f32 v47, v56, v57
	global_store_dwordx4 v[48:49], v[44:47], off
	v_pk_mul_f32 v[42:43], v[42:43], v[52:53] op_sel_hi:[1,0]
	v_pk_mul_f32 v[40:41], v[40:41], v[52:53] op_sel_hi:[1,0]
	v_pk_mul_f32 v[44:45], v[38:39], v[52:53] op_sel_hi:[1,0]
	v_pk_mul_f32 v[38:39], v[36:37], v[52:53] op_sel_hi:[1,0]
	v_cvt_pk_bf16_f32 v36, v40, v41
	v_cvt_pk_bf16_f32 v37, v42, v43
	s_mov_b64 s[0:1], 0xa0000
	v_cvt_pk_bf16_f32 v38, v38, v39
	v_cvt_pk_bf16_f32 v39, v44, v45
	global_store_dwordx4 v[54:55], v[36:39], off offset:256
	s_nop 0
	s_nop 0
	v_mov_b32_e32 v36, v250
	v_pk_mul_f32 v[32:33], v[32:33], v[36:37] op_sel_hi:[1,0]
	v_lshl_add_u64 v[38:39], v[142:143], 0, s[0:1]
	s_mov_b32 s0, 0xa0000
	v_pk_mul_f32 v[40:41], v[30:31], v[36:37] op_sel_hi:[1,0]
	v_pk_mul_f32 v[30:31], v[28:29], v[36:37] op_sel_hi:[1,0]
	v_cvt_pk_bf16_f32 v28, v32, v33
	v_add_co_u32_e32 v32, vcc, s0, v142
	v_pk_mul_f32 v[34:35], v[34:35], v[36:37] op_sel_hi:[1,0]
	s_nop 0
	v_addc_co_u32_e32 v33, vcc, 0, v143, vcc
	v_cvt_pk_bf16_f32 v29, v34, v35
	v_cvt_pk_bf16_f32 v30, v30, v31
	v_cvt_pk_bf16_f32 v31, v40, v41
	global_store_dwordx4 v[32:33], v[28:31], off
	v_pk_mul_f32 v[26:27], v[26:27], v[36:37] op_sel_hi:[1,0]
	v_pk_mul_f32 v[24:25], v[24:25], v[36:37] op_sel_hi:[1,0]
	v_pk_mul_f32 v[28:29], v[22:23], v[36:37] op_sel_hi:[1,0]
	v_pk_mul_f32 v[22:23], v[20:21], v[36:37] op_sel_hi:[1,0]
	v_cvt_pk_bf16_f32 v20, v24, v25
	v_cvt_pk_bf16_f32 v21, v26, v27
	s_mov_b64 s[0:1], 0xb0000
	v_cvt_pk_bf16_f32 v22, v22, v23
	v_cvt_pk_bf16_f32 v23, v28, v29
	global_store_dwordx4 v[38:39], v[20:23], off offset:256
	s_nop 0
	s_nop 0
	v_mov_b32_e32 v20, v251
	v_pk_mul_f32 v[16:17], v[16:17], v[20:21] op_sel_hi:[1,0]
	v_lshl_add_u64 v[22:23], v[142:143], 0, s[0:1]
	s_mov_b32 s0, 0xb0000
	v_pk_mul_f32 v[24:25], v[14:15], v[20:21] op_sel_hi:[1,0]
	v_pk_mul_f32 v[14:15], v[12:13], v[20:21] op_sel_hi:[1,0]
	v_cvt_pk_bf16_f32 v12, v16, v17
	v_add_co_u32_e32 v16, vcc, s0, v142
	v_pk_mul_f32 v[18:19], v[18:19], v[20:21] op_sel_hi:[1,0]
	s_nop 0
	v_addc_co_u32_e32 v17, vcc, 0, v143, vcc
	v_cvt_pk_bf16_f32 v13, v18, v19
	v_cvt_pk_bf16_f32 v14, v14, v15
	v_cvt_pk_bf16_f32 v15, v24, v25
	global_store_dwordx4 v[16:17], v[12:15], off
	s_andn2_b64 vcc, exec, s[38:39]
	v_pk_mul_f32 v[10:11], v[10:11], v[20:21] op_sel_hi:[1,0]
	v_pk_mul_f32 v[12:13], v[6:7], v[20:21] op_sel_hi:[1,0]
	v_pk_mul_f32 v[6:7], v[4:5], v[20:21] op_sel_hi:[1,0]
	v_pk_mul_f32 v[8:9], v[8:9], v[20:21] op_sel_hi:[1,0]
	s_nop 0
	v_cvt_pk_bf16_f32 v4, v8, v9
	v_cvt_pk_bf16_f32 v5, v10, v11
	v_cvt_pk_bf16_f32 v6, v6, v7
	v_cvt_pk_bf16_f32 v7, v12, v13
	global_store_dwordx4 v[22:23], v[4:7], off offset:256
	s_cbranch_vccnz .LBB0_172
	s_andn2_b64 vcc, exec, s[4:5]
	s_cbranch_vccnz .LBB0_171
	s_barrier
	s_branch .LBB0_171

.LBB0_197:
	s_ashr_i32 s43, s42, 31
	s_lshl_b64 s[10:11], s[42:43], 20
	s_add_u32 s44, s51, s10
	s_addc_u32 s45, s52, s11
	s_and_b64 s[10:11], s[38:39], exec
	s_cselect_b32 s3, s45, s27
	s_cselect_b32 s10, s44, s26
	s_ashr_i32 s29, s28, 31
	s_lshl_b64 s[36:37], s[28:29], 20
	s_add_u32 s46, s7, s36
	s_addc_u32 s47, s53, s37
	s_and_b64 s[36:37], s[38:39], exec
	s_cselect_b32 s11, s47, s35
	s_cselect_b32 s21, s46, s34
	s_add_u32 s26, s26, 0x80080
	s_addc_u32 s27, s27, 0
	s_add_u32 s22, s34, 0x100
	v_mov_b32_e32 v4, 0
	s_addc_u32 s29, s35, 0
	s_mov_b32 s33, -2
	v_mov_b32_e32 v5, v4
	v_mov_b32_e32 v6, v4
	v_mov_b32_e32 v7, v4
	v_mov_b32_e32 v8, v4
	v_mov_b32_e32 v9, v4
	v_mov_b32_e32 v10, v4
	v_mov_b32_e32 v11, v4
	v_mov_b32_e32 v20, v4
	v_mov_b32_e32 v21, v4
	v_mov_b32_e32 v22, v4
	v_mov_b32_e32 v23, v4
	v_mov_b32_e32 v24, v4
	v_mov_b32_e32 v25, v4
	v_mov_b32_e32 v26, v4
	v_mov_b32_e32 v27, v4
	v_mov_b32_e32 v36, v4
	v_mov_b32_e32 v37, v4
	v_mov_b32_e32 v38, v4
	v_mov_b32_e32 v39, v4
	v_mov_b32_e32 v40, v4
	v_mov_b32_e32 v41, v4
	v_mov_b32_e32 v42, v4
	v_mov_b32_e32 v43, v4
	v_mov_b32_e32 v52, v4
	v_mov_b32_e32 v53, v4
	v_mov_b32_e32 v54, v4
	v_mov_b32_e32 v55, v4
	v_mov_b32_e32 v56, v4
	v_mov_b32_e32 v57, v4
	v_mov_b32_e32 v58, v4
	v_mov_b32_e32 v59, v4
	v_mov_b32_e32 v12, v4
	v_mov_b32_e32 v13, v4
	v_mov_b32_e32 v14, v4
	v_mov_b32_e32 v15, v4
	v_mov_b32_e32 v16, v4
	v_mov_b32_e32 v17, v4
	v_mov_b32_e32 v18, v4
	v_mov_b32_e32 v19, v4
	v_mov_b32_e32 v28, v4
	v_mov_b32_e32 v29, v4
	v_mov_b32_e32 v30, v4
	v_mov_b32_e32 v31, v4
	v_mov_b32_e32 v32, v4
	v_mov_b32_e32 v33, v4
	v_mov_b32_e32 v34, v4
	v_mov_b32_e32 v35, v4
	v_mov_b32_e32 v44, v4
	v_mov_b32_e32 v45, v4
	v_mov_b32_e32 v46, v4
	v_mov_b32_e32 v47, v4
	v_mov_b32_e32 v48, v4
	v_mov_b32_e32 v49, v4
	v_mov_b32_e32 v50, v4
	v_mov_b32_e32 v51, v4
	v_mov_b32_e32 v60, v4
	v_mov_b32_e32 v61, v4
	v_mov_b32_e32 v62, v4
	v_mov_b32_e32 v63, v4
	v_mov_b32_e32 v64, v4
	v_mov_b32_e32 v65, v4
	v_mov_b32_e32 v66, v4
	v_mov_b32_e32 v67, v4
	v_mov_b32_e32 v68, v4
	v_mov_b32_e32 v69, v4
	v_mov_b32_e32 v70, v4
	v_mov_b32_e32 v71, v4
	v_mov_b32_e32 v72, v4
	v_mov_b32_e32 v73, v4
	v_mov_b32_e32 v74, v4
	v_mov_b32_e32 v75, v4
	v_mov_b32_e32 v84, v4
	v_mov_b32_e32 v85, v4
	v_mov_b32_e32 v86, v4
	v_mov_b32_e32 v87, v4
	v_mov_b32_e32 v88, v4
	v_mov_b32_e32 v89, v4
	v_mov_b32_e32 v90, v4
	v_mov_b32_e32 v91, v4
	v_mov_b32_e32 v100, v4
	v_mov_b32_e32 v101, v4
	v_mov_b32_e32 v102, v4
	v_mov_b32_e32 v103, v4
	v_mov_b32_e32 v104, v4
	v_mov_b32_e32 v105, v4
	v_mov_b32_e32 v106, v4
	v_mov_b32_e32 v107, v4
	v_mov_b32_e32 v116, v4
	v_mov_b32_e32 v117, v4
	v_mov_b32_e32 v118, v4
	v_mov_b32_e32 v119, v4
	v_mov_b32_e32 v120, v4
	v_mov_b32_e32 v121, v4
	v_mov_b32_e32 v122, v4
	v_mov_b32_e32 v123, v4
	v_mov_b32_e32 v76, v4
	v_mov_b32_e32 v77, v4
	v_mov_b32_e32 v78, v4
	v_mov_b32_e32 v79, v4
	v_mov_b32_e32 v80, v4
	v_mov_b32_e32 v81, v4
	v_mov_b32_e32 v82, v4
	v_mov_b32_e32 v83, v4
	v_mov_b32_e32 v92, v4
	v_mov_b32_e32 v93, v4
	v_mov_b32_e32 v94, v4
	v_mov_b32_e32 v95, v4
	v_mov_b32_e32 v96, v4
	v_mov_b32_e32 v97, v4
	v_mov_b32_e32 v98, v4
	v_mov_b32_e32 v99, v4
	v_mov_b32_e32 v108, v4
	v_mov_b32_e32 v109, v4
	v_mov_b32_e32 v110, v4
	v_mov_b32_e32 v111, v4
	v_mov_b32_e32 v112, v4
	v_mov_b32_e32 v113, v4
	v_mov_b32_e32 v114, v4
	v_mov_b32_e32 v115, v4
	v_mov_b32_e32 v124, v4
	v_mov_b32_e32 v125, v4
	v_mov_b32_e32 v126, v4
	v_mov_b32_e32 v127, v4
	v_mov_b32_e32 v128, v4
	v_mov_b32_e32 v129, v4
	v_mov_b32_e32 v130, v4
	v_mov_b32_e32 v131, v4
	v_lshl_add_u32 v142, s2, 8, v151
	v_ashrrev_i32_e32 v143, 31, v142
	v_lshl_add_u64 v[144:145], v[142:143], 2, s[40:41]
	global_load_dword v244, v[144:145], off
	global_load_dword v245, v[144:145], off offset:64
	global_load_dword v246, v[144:145], off offset:128
	global_load_dword v247, v[144:145], off offset:192
	global_load_dword v248, v[144:145], off offset:512
	global_load_dword v249, v[144:145], off offset:576
	global_load_dword v250, v[144:145], off offset:640
	global_load_dword v251, v[144:145], off offset:704

.LBB0_203:
	v_lshl_add_u32 v142, s2, 8, v151
	v_ashrrev_i32_e32 v143, 31, v142
	v_lshl_add_u64 v[144:145], v[142:143], 2, s[40:41]
	s_nop 0
	s_movk_i32 s0, 0x4000
	v_cmp_gt_i32_e32 vcc, s0, v142
	v_lshl_or_b32 v148, s1, 8, v158
	v_ashrrev_i32_e32 v149, 31, v148
	v_cndmask_b32_e32 v146, v154, v150, vcc
	v_cvt_f32_ubyte0_e32 v146, v146
	v_mul_f32_e32 v146, v160, v146
	v_exp_f32_e32 v146, v146
	v_lshlrev_b64 v[148:149], 1, v[148:149]
	s_movk_i32 s1, 0x3f80
	v_mov_b32_e32 v143, v244
	v_mul_f32_e32 v162, v143, v146
	v_mov_b64_e32 v[146:147], s[8:9]
	v_mad_i64_i32 v[164:165], s[2:3], v142, s6, v[146:147]
	v_lshl_add_u64 v[164:165], v[164:165], 0, v[148:149]
	v_pk_mul_f32 v[130:131], v[130:131], v[162:163] op_sel_hi:[1,0]
	v_pk_mul_f32 v[128:129], v[128:129], v[162:163] op_sel_hi:[1,0]
	v_pk_mul_f32 v[166:167], v[126:127], v[162:163] op_sel_hi:[1,0]
	v_pk_mul_f32 v[126:127], v[124:125], v[162:163] op_sel_hi:[1,0]
	v_cvt_pk_bf16_f32 v124, v128, v129
	v_cvt_pk_bf16_f32 v125, v130, v131
	v_pk_mul_f32 v[120:121], v[120:121], v[162:163] op_sel_hi:[1,0]
	v_cvt_pk_bf16_f32 v126, v126, v127
	v_cvt_pk_bf16_f32 v127, v166, v167
	global_store_dwordx4 v[164:165], v[124:127], off
	v_pk_mul_f32 v[122:123], v[122:123], v[162:163] op_sel_hi:[1,0]
	s_nop 0
	v_pk_mul_f32 v[124:125], v[118:119], v[162:163] op_sel_hi:[1,0]
	v_pk_mul_f32 v[118:119], v[116:117], v[162:163] op_sel_hi:[1,0]
	v_cvt_pk_bf16_f32 v116, v120, v121
	v_cvt_pk_bf16_f32 v117, v122, v123
	s_nop 0
	v_cvt_pk_bf16_f32 v118, v118, v119
	v_cvt_pk_bf16_f32 v119, v124, v125
	global_store_dwordx4 v[164:165], v[116:119], off offset:256
	s_nop 1
	v_or_b32_e32 v116, 16, v142
	v_ashrrev_i32_e32 v117, 31, v116
	v_lshl_add_u64 v[118:119], v[116:117], 2, s[40:41]
	s_nop 0
	v_cmp_gt_i32_e32 vcc, s0, v116
	s_nop 1
	v_cndmask_b32_e32 v120, v155, v153, vcc
	v_cvt_f32_ubyte0_e32 v118, v120
	v_mul_f32_e32 v118, v160, v118
	v_exp_f32_e32 v118, v118
	v_cmp_gt_i32_e32 vcc, s1, v142
	s_movk_i32 s1, 0x3f70
	v_mov_b32_e32 v117, v245
	v_mul_f32_e32 v118, v118, v117
	v_mad_i64_i32 v[116:117], s[2:3], v116, s6, v[146:147]
	v_lshl_add_u64 v[116:117], v[116:117], 0, v[148:149]
	v_pk_mul_f32 v[114:115], v[114:115], v[118:119] op_sel_hi:[1,0]
	v_pk_mul_f32 v[112:113], v[112:113], v[118:119] op_sel_hi:[1,0]
	v_pk_mul_f32 v[120:121], v[110:111], v[118:119] op_sel_hi:[1,0]
	v_pk_mul_f32 v[110:111], v[108:109], v[118:119] op_sel_hi:[1,0]
	v_cvt_pk_bf16_f32 v108, v112, v113
	v_cvt_pk_bf16_f32 v109, v114, v115
	v_pk_mul_f32 v[106:107], v[106:107], v[118:119] op_sel_hi:[1,0]
	v_cvt_pk_bf16_f32 v110, v110, v111
	v_cvt_pk_bf16_f32 v111, v120, v121
	global_store_dwordx4 v[116:117], v[108:111], off
	v_pk_mul_f32 v[104:105], v[104:105], v[118:119] op_sel_hi:[1,0]
	s_nop 0
	v_pk_mul_f32 v[108:109], v[102:103], v[118:119] op_sel_hi:[1,0]
	v_pk_mul_f32 v[102:103], v[100:101], v[118:119] op_sel_hi:[1,0]
	v_cvt_pk_bf16_f32 v100, v104, v105
	v_cvt_pk_bf16_f32 v101, v106, v107
	s_nop 0
	v_cvt_pk_bf16_f32 v102, v102, v103
	v_cvt_pk_bf16_f32 v103, v108, v109
	global_store_dwordx4 v[116:117], v[100:103], off offset:256
	s_nop 1
	v_or_b32_e32 v102, 32, v142
	v_ashrrev_i32_e32 v103, 31, v102
	v_lshl_add_u64 v[100:101], v[102:103], 2, s[40:41]
	s_nop 0
	v_mul_f32_e32 v100, v160, v156
	v_exp_f32_e32 v100, v100
	v_mad_i64_i32 v[102:103], s[2:3], v102, s6, v[146:147]
	v_lshl_add_u64 v[102:103], v[102:103], 0, v[148:149]
	v_mov_b32_e32 v101, v246
	v_mul_f32_e32 v104, v100, v101
	v_pk_mul_f32 v[98:99], v[98:99], v[104:105] op_sel_hi:[1,0]
	v_pk_mul_f32 v[96:97], v[96:97], v[104:105] op_sel_hi:[1,0]
	v_pk_mul_f32 v[106:107], v[94:95], v[104:105] op_sel_hi:[1,0]
	v_pk_mul_f32 v[94:95], v[92:93], v[104:105] op_sel_hi:[1,0]
	v_cvt_pk_bf16_f32 v92, v96, v97
	v_cvt_pk_bf16_f32 v93, v98, v99
	v_pk_mul_f32 v[88:89], v[88:89], v[104:105] op_sel_hi:[1,0]
	v_cvt_pk_bf16_f32 v94, v94, v95
	v_cvt_pk_bf16_f32 v95, v106, v107
	global_store_dwordx4 v[102:103], v[92:95], off
	v_pk_mul_f32 v[90:91], v[90:91], v[104:105] op_sel_hi:[1,0]
	s_nop 0
	v_pk_mul_f32 v[92:93], v[86:87], v[104:105] op_sel_hi:[1,0]
	v_pk_mul_f32 v[86:87], v[84:85], v[104:105] op_sel_hi:[1,0]
	v_cvt_pk_bf16_f32 v84, v88, v89
	v_cvt_pk_bf16_f32 v85, v90, v91
	s_nop 0
	v_cvt_pk_bf16_f32 v86, v86, v87
	v_cvt_pk_bf16_f32 v87, v92, v93
	global_store_dwordx4 v[102:103], v[84:87], off offset:256
	s_nop 1
	v_or_b32_e32 v84, 48, v142
	v_ashrrev_i32_e32 v85, 31, v84
	v_lshl_add_u64 v[86:87], v[84:85], 2, s[40:41]
	s_nop 0
	v_mul_f32_e32 v86, v160, v157
	v_exp_f32_e32 v87, v86
	v_mov_b32_e32 v85, v247
	v_mul_f32_e32 v86, v87, v85
	v_mad_i64_i32 v[84:85], s[2:3], v84, s6, v[146:147]
	v_lshl_add_u64 v[84:85], v[84:85], 0, v[148:149]
	v_pk_mul_f32 v[82:83], v[82:83], v[86:87] op_sel_hi:[1,0]
	v_pk_mul_f32 v[80:81], v[80:81], v[86:87] op_sel_hi:[1,0]
	v_pk_mul_f32 v[88:89], v[78:79], v[86:87] op_sel_hi:[1,0]
	v_pk_mul_f32 v[78:79], v[76:77], v[86:87] op_sel_hi:[1,0]
	v_cvt_pk_bf16_f32 v76, v80, v81
	v_cvt_pk_bf16_f32 v77, v82, v83
	v_pk_mul_f32 v[74:75], v[74:75], v[86:87] op_sel_hi:[1,0]
	v_cvt_pk_bf16_f32 v78, v78, v79
	v_cvt_pk_bf16_f32 v79, v88, v89
	global_store_dwordx4 v[84:85], v[76:79], off
	v_pk_mul_f32 v[72:73], v[72:73], v[86:87] op_sel_hi:[1,0]
	s_nop 0
	v_pk_mul_f32 v[76:77], v[70:71], v[86:87] op_sel_hi:[1,0]
	v_pk_mul_f32 v[70:71], v[68:69], v[86:87] op_sel_hi:[1,0]
	v_cvt_pk_bf16_f32 v68, v72, v73
	v_cvt_pk_bf16_f32 v69, v74, v75
	s_nop 0
	v_cvt_pk_bf16_f32 v70, v70, v71
	v_cvt_pk_bf16_f32 v71, v76, v77
	global_store_dwordx4 v[84:85], v[68:71], off offset:256
	s_nop 0
	s_nop 0
	v_cndmask_b32_e32 v68, v154, v150, vcc
	v_cvt_f32_ubyte0_e32 v68, v68
	v_mul_f32_e32 v68, v160, v68
	v_exp_f32_e32 v68, v68
	v_add_u32_e32 v69, 0x80, v142
	v_cmp_gt_i32_e32 vcc, s1, v142
	v_mov_b32_e32 v70, v248
	v_mul_f32_e32 v68, v68, v70
	v_mad_i64_i32 v[70:71], s[2:3], v69, s6, v[146:147]
	v_lshl_add_u64 v[70:71], v[70:71], 0, v[148:149]
	v_pk_mul_f32 v[66:67], v[66:67], v[68:69] op_sel_hi:[1,0]
	v_pk_mul_f32 v[64:65], v[64:65], v[68:69] op_sel_hi:[1,0]
	v_pk_mul_f32 v[72:73], v[62:63], v[68:69] op_sel_hi:[1,0]
	v_pk_mul_f32 v[62:63], v[60:61], v[68:69] op_sel_hi:[1,0]
	v_cvt_pk_bf16_f32 v60, v64, v65
	v_cvt_pk_bf16_f32 v61, v66, v67
	v_pk_mul_f32 v[58:59], v[58:59], v[68:69] op_sel_hi:[1,0]
	v_cvt_pk_bf16_f32 v62, v62, v63
	v_cvt_pk_bf16_f32 v63, v72, v73
	global_store_dwordx4 v[70:71], v[60:63], off
	v_pk_mul_f32 v[56:57], v[56:57], v[68:69] op_sel_hi:[1,0]
	s_nop 0
	v_pk_mul_f32 v[60:61], v[54:55], v[68:69] op_sel_hi:[1,0]
	v_pk_mul_f32 v[54:55], v[52:53], v[68:69] op_sel_hi:[1,0]
	v_cvt_pk_bf16_f32 v52, v56, v57
	v_cvt_pk_bf16_f32 v53, v58, v59
	s_nop 0
	v_cvt_pk_bf16_f32 v54, v54, v55
	v_cvt_pk_bf16_f32 v55, v60, v61
	global_store_dwordx4 v[70:71], v[52:55], off offset:256
	s_nop 0
	s_nop 0
	v_cndmask_b32_e32 v52, v155, v153, vcc
	v_cvt_f32_ubyte0_e32 v52, v52
	v_mul_f32_e32 v52, v160, v52
	v_exp_f32_e32 v52, v52
	v_add_u32_e32 v53, 0x90, v142
	s_andn2_b64 vcc, exec, s[38:39]
	v_mov_b32_e32 v54, v249
	v_mul_f32_e32 v52, v52, v54
	v_mad_i64_i32 v[54:55], s[2:3], v53, s6, v[146:147]
	v_lshl_add_u64 v[54:55], v[54:55], 0, v[148:149]
	v_pk_mul_f32 v[50:51], v[50:51], v[52:53] op_sel_hi:[1,0]
	v_pk_mul_f32 v[48:49], v[48:49], v[52:53] op_sel_hi:[1,0]
	v_pk_mul_f32 v[56:57], v[46:47], v[52:53] op_sel_hi:[1,0]
	v_pk_mul_f32 v[46:47], v[44:45], v[52:53] op_sel_hi:[1,0]
	v_cvt_pk_bf16_f32 v44, v48, v49
	v_cvt_pk_bf16_f32 v45, v50, v51
	v_pk_mul_f32 v[42:43], v[42:43], v[52:53] op_sel_hi:[1,0]
	v_cvt_pk_bf16_f32 v46, v46, v47
	v_cvt_pk_bf16_f32 v47, v56, v57
	global_store_dwordx4 v[54:55], v[44:47], off
	v_pk_mul_f32 v[40:41], v[40:41], v[52:53] op_sel_hi:[1,0]
	s_nop 0
	v_pk_mul_f32 v[44:45], v[38:39], v[52:53] op_sel_hi:[1,0]
	v_pk_mul_f32 v[38:39], v[36:37], v[52:53] op_sel_hi:[1,0]
	v_cvt_pk_bf16_f32 v36, v40, v41
	v_cvt_pk_bf16_f32 v37, v42, v43
	s_nop 0
	v_cvt_pk_bf16_f32 v38, v38, v39
	v_cvt_pk_bf16_f32 v39, v44, v45
	global_store_dwordx4 v[54:55], v[36:39], off offset:256
	s_nop 0
	s_nop 0
	v_add_u32_e32 v37, 0xa0, v142
	v_mad_i64_i32 v[38:39], s[2:3], v37, s6, v[146:147]
	v_lshl_add_u64 v[38:39], v[38:39], 0, v[148:149]
	v_mov_b32_e32 v36, v250
	v_mul_f32_e32 v36, v100, v36
	v_pk_mul_f32 v[34:35], v[34:35], v[36:37] op_sel_hi:[1,0]
	v_pk_mul_f32 v[32:33], v[32:33], v[36:37] op_sel_hi:[1,0]
	v_pk_mul_f32 v[40:41], v[30:31], v[36:37] op_sel_hi:[1,0]
	v_pk_mul_f32 v[30:31], v[28:29], v[36:37] op_sel_hi:[1,0]
	v_cvt_pk_bf16_f32 v28, v32, v33
	v_cvt_pk_bf16_f32 v29, v34, v35
	v_pk_mul_f32 v[26:27], v[26:27], v[36:37] op_sel_hi:[1,0]
	v_cvt_pk_bf16_f32 v30, v30, v31
	v_cvt_pk_bf16_f32 v31, v40, v41
	global_store_dwordx4 v[38:39], v[28:31], off
	v_pk_mul_f32 v[24:25], v[24:25], v[36:37] op_sel_hi:[1,0]
	s_nop 0
	v_pk_mul_f32 v[28:29], v[22:23], v[36:37] op_sel_hi:[1,0]
	v_pk_mul_f32 v[22:23], v[20:21], v[36:37] op_sel_hi:[1,0]
	v_cvt_pk_bf16_f32 v20, v24, v25
	v_cvt_pk_bf16_f32 v21, v26, v27
	s_nop 0
	v_cvt_pk_bf16_f32 v22, v22, v23
	v_cvt_pk_bf16_f32 v23, v28, v29
	global_store_dwordx4 v[38:39], v[20:23], off offset:256
	s_nop 0
	s_nop 0
	v_add_u32_e32 v21, 0xb0, v142
	v_mad_i64_i32 v[22:23], s[2:3], v21, s6, v[146:147]
	v_lshl_add_u64 v[22:23], v[22:23], 0, v[148:149]
	s_mov_b64 s[2:3], -1
	v_mov_b32_e32 v20, v251
	v_mul_f32_e32 v20, v87, v20
	v_pk_mul_f32 v[18:19], v[18:19], v[20:21] op_sel_hi:[1,0]
	v_pk_mul_f32 v[16:17], v[16:17], v[20:21] op_sel_hi:[1,0]
	v_pk_mul_f32 v[24:25], v[14:15], v[20:21] op_sel_hi:[1,0]
	v_pk_mul_f32 v[14:15], v[12:13], v[20:21] op_sel_hi:[1,0]
	v_cvt_pk_bf16_f32 v12, v16, v17
	v_cvt_pk_bf16_f32 v13, v18, v19
	v_pk_mul_f32 v[10:11], v[10:11], v[20:21] op_sel_hi:[1,0]
	v_cvt_pk_bf16_f32 v14, v14, v15
	v_cvt_pk_bf16_f32 v15, v24, v25
	global_store_dwordx4 v[22:23], v[12:15], off
	v_pk_mul_f32 v[8:9], v[8:9], v[20:21] op_sel_hi:[1,0]
	s_nop 0
	v_pk_mul_f32 v[12:13], v[6:7], v[20:21] op_sel_hi:[1,0]
	v_pk_mul_f32 v[6:7], v[4:5], v[20:21] op_sel_hi:[1,0]
	v_cvt_pk_bf16_f32 v4, v8, v9
	v_cvt_pk_bf16_f32 v5, v10, v11
	s_nop 0
	v_cvt_pk_bf16_f32 v6, v6, v7
	v_cvt_pk_bf16_f32 v7, v12, v13
	global_store_dwordx4 v[22:23], v[4:7], off offset:256
	s_cbranch_vccnz .LBB0_194
	s_andn2_b64 vcc, exec, s[4:5]
	s_cbranch_vccnz .LBB0_193
	s_barrier
	s_branch .LBB0_193

.LBB0_900:
	s_ashr_i32 s49, s48, 31
	s_lshl_b64 s[10:11], s[48:49], 20
	s_add_u32 s50, s34, s10
	s_addc_u32 s51, s35, s11
	s_and_b64 s[10:11], s[38:39], exec
	s_cselect_b32 s5, s51, s9
	s_cselect_b32 s7, s50, s8
	s_ashr_i32 s47, s46, 31
	s_lshl_b64 s[10:11], s[46:47], 20
	s_add_u32 s52, s37, s10
	s_addc_u32 s53, s54, s11
	s_and_b64 s[10:11], s[38:39], exec
	s_cselect_b32 s10, s53, s13
	s_cselect_b32 s11, s52, s12
	s_add_u32 s8, s8, 0x80080
	s_addc_u32 s9, s9, 0
	s_add_u32 s21, s12, 0x100
	v_mov_b32_e32 v4, 0
	s_addc_u32 s22, s13, 0
	s_mov_b32 s33, -2
	v_mov_b32_e32 v5, v4
	v_mov_b32_e32 v6, v4
	v_mov_b32_e32 v7, v4
	v_mov_b32_e32 v8, v4
	v_mov_b32_e32 v9, v4
	v_mov_b32_e32 v10, v4
	v_mov_b32_e32 v11, v4
	v_mov_b32_e32 v20, v4
	v_mov_b32_e32 v21, v4
	v_mov_b32_e32 v22, v4
	v_mov_b32_e32 v23, v4
	v_mov_b32_e32 v24, v4
	v_mov_b32_e32 v25, v4
	v_mov_b32_e32 v26, v4
	v_mov_b32_e32 v27, v4
	v_mov_b32_e32 v36, v4
	v_mov_b32_e32 v37, v4
	v_mov_b32_e32 v38, v4
	v_mov_b32_e32 v39, v4
	v_mov_b32_e32 v40, v4
	v_mov_b32_e32 v41, v4
	v_mov_b32_e32 v42, v4
	v_mov_b32_e32 v43, v4
	v_mov_b32_e32 v52, v4
	v_mov_b32_e32 v53, v4
	v_mov_b32_e32 v54, v4
	v_mov_b32_e32 v55, v4
	v_mov_b32_e32 v56, v4
	v_mov_b32_e32 v57, v4
	v_mov_b32_e32 v58, v4
	v_mov_b32_e32 v59, v4
	v_mov_b32_e32 v12, v4
	v_mov_b32_e32 v13, v4
	v_mov_b32_e32 v14, v4
	v_mov_b32_e32 v15, v4
	v_mov_b32_e32 v16, v4
	v_mov_b32_e32 v17, v4
	v_mov_b32_e32 v18, v4
	v_mov_b32_e32 v19, v4
	v_mov_b32_e32 v28, v4
	v_mov_b32_e32 v29, v4
	v_mov_b32_e32 v30, v4
	v_mov_b32_e32 v31, v4
	v_mov_b32_e32 v32, v4
	v_mov_b32_e32 v33, v4
	v_mov_b32_e32 v34, v4
	v_mov_b32_e32 v35, v4
	v_mov_b32_e32 v44, v4
	v_mov_b32_e32 v45, v4
	v_mov_b32_e32 v46, v4
	v_mov_b32_e32 v47, v4
	v_mov_b32_e32 v48, v4
	v_mov_b32_e32 v49, v4
	v_mov_b32_e32 v50, v4
	v_mov_b32_e32 v51, v4
	v_mov_b32_e32 v60, v4
	v_mov_b32_e32 v61, v4
	v_mov_b32_e32 v62, v4
	v_mov_b32_e32 v63, v4
	v_mov_b32_e32 v64, v4
	v_mov_b32_e32 v65, v4
	v_mov_b32_e32 v66, v4
	v_mov_b32_e32 v67, v4
	v_mov_b32_e32 v68, v4
	v_mov_b32_e32 v69, v4
	v_mov_b32_e32 v70, v4
	v_mov_b32_e32 v71, v4
	v_mov_b32_e32 v72, v4
	v_mov_b32_e32 v73, v4
	v_mov_b32_e32 v74, v4
	v_mov_b32_e32 v75, v4
	v_mov_b32_e32 v84, v4
	v_mov_b32_e32 v85, v4
	v_mov_b32_e32 v86, v4
	v_mov_b32_e32 v87, v4
	v_mov_b32_e32 v88, v4
	v_mov_b32_e32 v89, v4
	v_mov_b32_e32 v90, v4
	v_mov_b32_e32 v91, v4
	v_mov_b32_e32 v100, v4
	v_mov_b32_e32 v101, v4
	v_mov_b32_e32 v102, v4
	v_mov_b32_e32 v103, v4
	v_mov_b32_e32 v104, v4
	v_mov_b32_e32 v105, v4
	v_mov_b32_e32 v106, v4
	v_mov_b32_e32 v107, v4
	v_mov_b32_e32 v116, v4
	v_mov_b32_e32 v117, v4
	v_mov_b32_e32 v118, v4
	v_mov_b32_e32 v119, v4
	v_mov_b32_e32 v120, v4
	v_mov_b32_e32 v121, v4
	v_mov_b32_e32 v122, v4
	v_mov_b32_e32 v123, v4
	v_mov_b32_e32 v76, v4
	v_mov_b32_e32 v77, v4
	v_mov_b32_e32 v78, v4
	v_mov_b32_e32 v79, v4
	v_mov_b32_e32 v80, v4
	v_mov_b32_e32 v81, v4
	v_mov_b32_e32 v82, v4
	v_mov_b32_e32 v83, v4
	v_mov_b32_e32 v92, v4
	v_mov_b32_e32 v93, v4
	v_mov_b32_e32 v94, v4
	v_mov_b32_e32 v95, v4
	v_mov_b32_e32 v96, v4
	v_mov_b32_e32 v97, v4
	v_mov_b32_e32 v98, v4
	v_mov_b32_e32 v99, v4
	v_mov_b32_e32 v108, v4
	v_mov_b32_e32 v109, v4
	v_mov_b32_e32 v110, v4
	v_mov_b32_e32 v111, v4
	v_mov_b32_e32 v112, v4
	v_mov_b32_e32 v113, v4
	v_mov_b32_e32 v114, v4
	v_mov_b32_e32 v115, v4
	v_mov_b32_e32 v124, v4
	v_mov_b32_e32 v125, v4
	v_mov_b32_e32 v126, v4
	v_mov_b32_e32 v127, v4
	v_mov_b32_e32 v128, v4
	v_mov_b32_e32 v129, v4
	v_mov_b32_e32 v130, v4
	v_mov_b32_e32 v131, v4
	v_lshl_add_u32 v148, s4, 8, v150
	v_ashrrev_i32_e32 v149, 31, v148
	v_lshl_add_u64 v[144:145], v[148:149], 2, s[40:41]
	global_load_dword v244, v[144:145], off
	global_load_dword v245, v[144:145], off offset:64
	global_load_dword v246, v[144:145], off offset:128
	global_load_dword v247, v[144:145], off offset:192
	global_load_dword v248, v[144:145], off offset:512
	global_load_dword v249, v[144:145], off offset:576
	global_load_dword v250, v[144:145], off offset:640
	global_load_dword v251, v[144:145], off offset:704

.LBB0_904:
	v_lshl_add_u32 v148, s4, 8, v150
	v_ashrrev_i32_e32 v149, 31, v148
	v_lshl_add_u64 v[144:145], v[148:149], 2, s[40:41]
	s_nop 0
	v_lshl_or_b32 v142, s1, 8, v152
	v_ashrrev_i32_e32 v143, 31, v142
	v_lshlrev_b64 v[146:147], 14, v[148:149]
	v_lshl_add_u64 v[156:157], s[42:43], 0, v[146:147]
	v_lshlrev_b64 v[146:147], 1, v[142:143]
	v_lshl_add_u64 v[142:143], v[156:157], 0, v[146:147]
	s_mov_b32 s1, 0x200000
	s_mov_b64 s[4:5], 0x200000
	s_movk_i32 s33, 0x7ff
	v_mov_b32_e32 v154, v244
	v_pk_mul_f32 v[130:131], v[130:131], v[154:155] op_sel_hi:[1,0]
	v_pk_mul_f32 v[128:129], v[128:129], v[154:155] op_sel_hi:[1,0]
	v_pk_mul_f32 v[126:127], v[126:127], v[154:155] op_sel_hi:[1,0]
	v_pk_mul_f32 v[124:125], v[124:125], v[154:155] op_sel_hi:[1,0]
	v_max_f32_e32 v129, 0, v129
	v_max_f32_e32 v128, 0, v128
	v_max_f32_e32 v131, 0, v131
	v_max_f32_e32 v130, 0, v130
	v_max_f32_e32 v125, 0, v125
	v_max_f32_e32 v124, 0, v124
	v_max_f32_e32 v127, 0, v127
	v_max_f32_e32 v126, 0, v126
	v_pk_mul_f32 v[120:121], v[120:121], v[154:155] op_sel_hi:[1,0]
	v_pk_mul_f32 v[118:119], v[118:119], v[154:155] op_sel_hi:[1,0]
	v_pk_mul_f32 v[116:117], v[116:117], v[154:155] op_sel_hi:[1,0]
	v_pk_mul_f32 v[130:131], v[130:131], v[130:131]
	v_pk_mul_f32 v[128:129], v[128:129], v[128:129]
	v_pk_mul_f32 v[156:157], v[126:127], v[126:127]
	v_pk_mul_f32 v[126:127], v[124:125], v[124:125]
	v_cvt_pk_bf16_f32 v124, v128, v129
	v_cvt_pk_bf16_f32 v125, v130, v131
	v_pk_mul_f32 v[122:123], v[122:123], v[154:155] op_sel_hi:[1,0]
	v_max_f32_e32 v121, 0, v121
	v_max_f32_e32 v120, 0, v120
	v_max_f32_e32 v117, 0, v117
	v_max_f32_e32 v116, 0, v116
	v_max_f32_e32 v119, 0, v119
	v_max_f32_e32 v118, 0, v118
	v_cvt_pk_bf16_f32 v126, v126, v127
	v_cvt_pk_bf16_f32 v127, v156, v157
	global_store_dwordx4 v[142:143], v[124:127], off
	v_max_f32_e32 v123, 0, v123
	v_max_f32_e32 v122, 0, v122
	v_pk_mul_f32 v[120:121], v[120:121], v[120:121]
	v_pk_mul_f32 v[124:125], v[118:119], v[118:119]
	v_pk_mul_f32 v[118:119], v[116:117], v[116:117]
	v_cvt_pk_bf16_f32 v116, v120, v121
	v_pk_mul_f32 v[122:123], v[122:123], v[122:123]
	s_nop 0
	v_cvt_pk_bf16_f32 v117, v122, v123
	v_cvt_pk_bf16_f32 v118, v118, v119
	v_cvt_pk_bf16_f32 v119, v124, v125
	global_store_dwordx4 v[142:143], v[116:119], off offset:256
	s_nop 1
	v_or_b32_e32 v116, 16, v148
	v_ashrrev_i32_e32 v117, 31, v116
	v_lshl_add_u64 v[118:119], v[116:117], 2, s[40:41]
	s_nop 0
	v_lshlrev_b64 v[116:117], 14, v[116:117]
	v_lshl_add_u64 v[116:117], s[42:43], 0, v[116:117]
	v_lshl_add_u64 v[116:117], v[116:117], 0, v[146:147]
	v_mov_b32_e32 v118, v245
	v_pk_mul_f32 v[114:115], v[114:115], v[118:119] op_sel_hi:[1,0]
	v_pk_mul_f32 v[112:113], v[112:113], v[118:119] op_sel_hi:[1,0]
	v_pk_mul_f32 v[110:111], v[110:111], v[118:119] op_sel_hi:[1,0]
	v_pk_mul_f32 v[108:109], v[108:109], v[118:119] op_sel_hi:[1,0]
	v_max_f32_e32 v113, 0, v113
	v_max_f32_e32 v112, 0, v112
	v_max_f32_e32 v115, 0, v115
	v_max_f32_e32 v114, 0, v114
	v_max_f32_e32 v109, 0, v109
	v_max_f32_e32 v108, 0, v108
	v_max_f32_e32 v111, 0, v111
	v_max_f32_e32 v110, 0, v110
	v_pk_mul_f32 v[104:105], v[104:105], v[118:119] op_sel_hi:[1,0]
	v_pk_mul_f32 v[102:103], v[102:103], v[118:119] op_sel_hi:[1,0]
	v_pk_mul_f32 v[100:101], v[100:101], v[118:119] op_sel_hi:[1,0]
	v_pk_mul_f32 v[114:115], v[114:115], v[114:115]
	v_pk_mul_f32 v[112:113], v[112:113], v[112:113]
	v_pk_mul_f32 v[120:121], v[110:111], v[110:111]
	v_pk_mul_f32 v[110:111], v[108:109], v[108:109]
	v_cvt_pk_bf16_f32 v108, v112, v113
	v_cvt_pk_bf16_f32 v109, v114, v115
	v_pk_mul_f32 v[106:107], v[106:107], v[118:119] op_sel_hi:[1,0]
	v_max_f32_e32 v105, 0, v105
	v_max_f32_e32 v104, 0, v104
	v_max_f32_e32 v101, 0, v101
	v_max_f32_e32 v100, 0, v100
	v_max_f32_e32 v103, 0, v103
	v_max_f32_e32 v102, 0, v102
	v_cvt_pk_bf16_f32 v110, v110, v111
	v_cvt_pk_bf16_f32 v111, v120, v121
	global_store_dwordx4 v[116:117], v[108:111], off
	v_max_f32_e32 v107, 0, v107
	v_max_f32_e32 v106, 0, v106
	v_pk_mul_f32 v[104:105], v[104:105], v[104:105]
	v_pk_mul_f32 v[108:109], v[102:103], v[102:103]
	v_pk_mul_f32 v[102:103], v[100:101], v[100:101]
	v_cvt_pk_bf16_f32 v100, v104, v105
	v_pk_mul_f32 v[106:107], v[106:107], v[106:107]
	s_nop 0
	v_cvt_pk_bf16_f32 v101, v106, v107
	v_cvt_pk_bf16_f32 v102, v102, v103
	v_cvt_pk_bf16_f32 v103, v108, v109
	global_store_dwordx4 v[116:117], v[100:103], off offset:256
	s_nop 1
	v_or_b32_e32 v100, 32, v148
	v_ashrrev_i32_e32 v101, 31, v100
	v_lshl_add_u64 v[102:103], v[100:101], 2, s[40:41]
	s_nop 0
	v_lshlrev_b64 v[100:101], 14, v[100:101]
	v_lshl_add_u64 v[100:101], s[42:43], 0, v[100:101]
	v_lshl_add_u64 v[100:101], v[100:101], 0, v[146:147]
	v_mov_b32_e32 v102, v246
	v_pk_mul_f32 v[98:99], v[98:99], v[102:103] op_sel_hi:[1,0]
	v_pk_mul_f32 v[96:97], v[96:97], v[102:103] op_sel_hi:[1,0]
	v_pk_mul_f32 v[94:95], v[94:95], v[102:103] op_sel_hi:[1,0]
	v_pk_mul_f32 v[92:93], v[92:93], v[102:103] op_sel_hi:[1,0]
	v_max_f32_e32 v97, 0, v97
	v_max_f32_e32 v96, 0, v96
	v_max_f32_e32 v99, 0, v99
	v_max_f32_e32 v98, 0, v98
	v_max_f32_e32 v93, 0, v93
	v_max_f32_e32 v92, 0, v92
	v_max_f32_e32 v95, 0, v95
	v_max_f32_e32 v94, 0, v94
	v_pk_mul_f32 v[88:89], v[88:89], v[102:103] op_sel_hi:[1,0]
	v_pk_mul_f32 v[86:87], v[86:87], v[102:103] op_sel_hi:[1,0]
	v_pk_mul_f32 v[84:85], v[84:85], v[102:103] op_sel_hi:[1,0]
	v_pk_mul_f32 v[98:99], v[98:99], v[98:99]
	v_pk_mul_f32 v[96:97], v[96:97], v[96:97]
	v_pk_mul_f32 v[104:105], v[94:95], v[94:95]
	v_pk_mul_f32 v[94:95], v[92:93], v[92:93]
	v_cvt_pk_bf16_f32 v92, v96, v97
	v_cvt_pk_bf16_f32 v93, v98, v99
	v_pk_mul_f32 v[90:91], v[90:91], v[102:103] op_sel_hi:[1,0]
	v_max_f32_e32 v89, 0, v89
	v_max_f32_e32 v88, 0, v88
	v_max_f32_e32 v85, 0, v85
	v_max_f32_e32 v84, 0, v84
	v_max_f32_e32 v87, 0, v87
	v_max_f32_e32 v86, 0, v86
	v_cvt_pk_bf16_f32 v94, v94, v95
	v_cvt_pk_bf16_f32 v95, v104, v105
	global_store_dwordx4 v[100:101], v[92:95], off
	v_max_f32_e32 v91, 0, v91
	v_max_f32_e32 v90, 0, v90
	v_pk_mul_f32 v[88:89], v[88:89], v[88:89]
	v_pk_mul_f32 v[92:93], v[86:87], v[86:87]
	v_pk_mul_f32 v[86:87], v[84:85], v[84:85]
	v_cvt_pk_bf16_f32 v84, v88, v89
	v_pk_mul_f32 v[90:91], v[90:91], v[90:91]
	s_nop 0
	v_cvt_pk_bf16_f32 v85, v90, v91
	v_cvt_pk_bf16_f32 v86, v86, v87
	v_cvt_pk_bf16_f32 v87, v92, v93
	global_store_dwordx4 v[100:101], v[84:87], off offset:256
	s_nop 1
	v_or_b32_e32 v84, 48, v148
	v_ashrrev_i32_e32 v85, 31, v84
	v_lshl_add_u64 v[86:87], v[84:85], 2, s[40:41]
	s_nop 0
	v_lshlrev_b64 v[84:85], 14, v[84:85]
	v_lshl_add_u64 v[84:85], s[42:43], 0, v[84:85]
	v_lshl_add_u64 v[84:85], v[84:85], 0, v[146:147]
	v_mov_b32_e32 v86, v247
	v_pk_mul_f32 v[82:83], v[82:83], v[86:87] op_sel_hi:[1,0]
	v_pk_mul_f32 v[80:81], v[80:81], v[86:87] op_sel_hi:[1,0]
	v_pk_mul_f32 v[78:79], v[78:79], v[86:87] op_sel_hi:[1,0]
	v_pk_mul_f32 v[76:77], v[76:77], v[86:87] op_sel_hi:[1,0]
	v_max_f32_e32 v81, 0, v81
	v_max_f32_e32 v80, 0, v80
	v_max_f32_e32 v83, 0, v83
	v_max_f32_e32 v82, 0, v82
	v_max_f32_e32 v77, 0, v77
	v_max_f32_e32 v76, 0, v76
	v_max_f32_e32 v79, 0, v79
	v_max_f32_e32 v78, 0, v78
	v_pk_mul_f32 v[70:71], v[70:71], v[86:87] op_sel_hi:[1,0]
	v_pk_mul_f32 v[68:69], v[68:69], v[86:87] op_sel_hi:[1,0]
	v_pk_mul_f32 v[82:83], v[82:83], v[82:83]
	v_pk_mul_f32 v[80:81], v[80:81], v[80:81]
	v_pk_mul_f32 v[88:89], v[78:79], v[78:79]
	v_pk_mul_f32 v[78:79], v[76:77], v[76:77]
	v_cvt_pk_bf16_f32 v76, v80, v81
	v_cvt_pk_bf16_f32 v77, v82, v83
	v_pk_mul_f32 v[74:75], v[74:75], v[86:87] op_sel_hi:[1,0]
	v_pk_mul_f32 v[72:73], v[72:73], v[86:87] op_sel_hi:[1,0]
	v_max_f32_e32 v69, 0, v69
	v_max_f32_e32 v68, 0, v68
	v_max_f32_e32 v71, 0, v71
	v_max_f32_e32 v70, 0, v70
	v_cvt_pk_bf16_f32 v78, v78, v79
	v_cvt_pk_bf16_f32 v79, v88, v89
	global_store_dwordx4 v[84:85], v[76:79], off
	v_max_f32_e32 v73, 0, v73
	v_max_f32_e32 v72, 0, v72
	v_max_f32_e32 v75, 0, v75
	v_max_f32_e32 v74, 0, v74
	v_pk_mul_f32 v[76:77], v[70:71], v[70:71]
	v_pk_mul_f32 v[70:71], v[68:69], v[68:69]
	v_pk_mul_f32 v[74:75], v[74:75], v[74:75]
	v_pk_mul_f32 v[72:73], v[72:73], v[72:73]
	s_nop 0
	v_cvt_pk_bf16_f32 v68, v72, v73
	v_cvt_pk_bf16_f32 v69, v74, v75
	v_cvt_pk_bf16_f32 v70, v70, v71
	v_cvt_pk_bf16_f32 v71, v76, v77
	global_store_dwordx4 v[84:85], v[68:71], off offset:256
	s_nop 0
	s_nop 0
	v_mov_b32_e32 v70, v248
	v_pk_mul_f32 v[64:65], v[64:65], v[70:71] op_sel_hi:[1,0]
	v_pk_mul_f32 v[62:63], v[62:63], v[70:71] op_sel_hi:[1,0]
	v_pk_mul_f32 v[60:61], v[60:61], v[70:71] op_sel_hi:[1,0]
	v_max_f32_e32 v65, 0, v65
	v_max_f32_e32 v64, 0, v64
	v_pk_mul_f32 v[66:67], v[66:67], v[70:71] op_sel_hi:[1,0]
	v_max_f32_e32 v61, 0, v61
	v_max_f32_e32 v60, 0, v60
	v_max_f32_e32 v63, 0, v63
	v_max_f32_e32 v62, 0, v62
	v_pk_mul_f32 v[64:65], v[64:65], v[64:65]
	v_max_f32_e32 v67, 0, v67
	v_max_f32_e32 v66, 0, v66
	v_pk_mul_f32 v[72:73], v[62:63], v[62:63]
	v_pk_mul_f32 v[62:63], v[60:61], v[60:61]
	v_cvt_pk_bf16_f32 v60, v64, v65
	v_add_co_u32_e32 v64, vcc, s1, v142
	v_pk_mul_f32 v[54:55], v[54:55], v[70:71] op_sel_hi:[1,0]
	v_pk_mul_f32 v[52:53], v[52:53], v[70:71] op_sel_hi:[1,0]
	v_pk_mul_f32 v[66:67], v[66:67], v[66:67]
	v_addc_co_u32_e32 v65, vcc, 0, v143, vcc
	v_cvt_pk_bf16_f32 v61, v66, v67
	v_pk_mul_f32 v[58:59], v[58:59], v[70:71] op_sel_hi:[1,0]
	v_pk_mul_f32 v[56:57], v[56:57], v[70:71] op_sel_hi:[1,0]
	v_max_f32_e32 v53, 0, v53
	v_max_f32_e32 v52, 0, v52
	v_max_f32_e32 v55, 0, v55
	v_max_f32_e32 v54, 0, v54
	v_lshl_add_u64 v[68:69], v[142:143], 0, s[4:5]
	v_cvt_pk_bf16_f32 v62, v62, v63
	v_cvt_pk_bf16_f32 v63, v72, v73
	global_store_dwordx4 v[64:65], v[60:63], off
	v_max_f32_e32 v57, 0, v57
	v_max_f32_e32 v56, 0, v56
	v_max_f32_e32 v59, 0, v59
	v_max_f32_e32 v58, 0, v58
	v_pk_mul_f32 v[60:61], v[54:55], v[54:55]
	v_pk_mul_f32 v[54:55], v[52:53], v[52:53]
	v_pk_mul_f32 v[58:59], v[58:59], v[58:59]
	v_pk_mul_f32 v[56:57], v[56:57], v[56:57]
	s_mov_b32 s1, 0x240000
	v_cvt_pk_bf16_f32 v52, v56, v57
	v_cvt_pk_bf16_f32 v53, v58, v59
	v_cvt_pk_bf16_f32 v54, v54, v55
	v_cvt_pk_bf16_f32 v55, v60, v61
	global_store_dwordx4 v[68:69], v[52:55], off offset:256
	s_nop 0
	s_mov_b64 s[4:5], 0x240000
	v_lshl_add_u64 v[52:53], v[142:143], 0, s[4:5]
	s_mov_b64 s[4:5], 0x280000
	v_mov_b32_e32 v54, v249
	v_pk_mul_f32 v[48:49], v[48:49], v[54:55] op_sel_hi:[1,0]
	v_pk_mul_f32 v[46:47], v[46:47], v[54:55] op_sel_hi:[1,0]
	v_pk_mul_f32 v[44:45], v[44:45], v[54:55] op_sel_hi:[1,0]
	v_max_f32_e32 v49, 0, v49
	v_max_f32_e32 v48, 0, v48
	v_pk_mul_f32 v[50:51], v[50:51], v[54:55] op_sel_hi:[1,0]
	v_max_f32_e32 v45, 0, v45
	v_max_f32_e32 v44, 0, v44
	v_max_f32_e32 v47, 0, v47
	v_max_f32_e32 v46, 0, v46
	v_pk_mul_f32 v[48:49], v[48:49], v[48:49]
	v_max_f32_e32 v51, 0, v51
	v_max_f32_e32 v50, 0, v50
	v_pk_mul_f32 v[56:57], v[46:47], v[46:47]
	v_pk_mul_f32 v[46:47], v[44:45], v[44:45]
	v_cvt_pk_bf16_f32 v44, v48, v49
	v_add_co_u32_e32 v48, vcc, s1, v142
	v_pk_mul_f32 v[38:39], v[38:39], v[54:55] op_sel_hi:[1,0]
	v_pk_mul_f32 v[36:37], v[36:37], v[54:55] op_sel_hi:[1,0]
	v_pk_mul_f32 v[50:51], v[50:51], v[50:51]
	v_addc_co_u32_e32 v49, vcc, 0, v143, vcc
	v_cvt_pk_bf16_f32 v45, v50, v51
	v_pk_mul_f32 v[42:43], v[42:43], v[54:55] op_sel_hi:[1,0]
	v_pk_mul_f32 v[40:41], v[40:41], v[54:55] op_sel_hi:[1,0]
	v_max_f32_e32 v37, 0, v37
	v_max_f32_e32 v36, 0, v36
	v_max_f32_e32 v39, 0, v39
	v_max_f32_e32 v38, 0, v38
	v_cvt_pk_bf16_f32 v46, v46, v47
	v_cvt_pk_bf16_f32 v47, v56, v57
	global_store_dwordx4 v[48:49], v[44:47], off
	v_max_f32_e32 v41, 0, v41
	v_max_f32_e32 v40, 0, v40
	v_max_f32_e32 v43, 0, v43
	v_max_f32_e32 v42, 0, v42
	v_pk_mul_f32 v[44:45], v[38:39], v[38:39]
	v_pk_mul_f32 v[38:39], v[36:37], v[36:37]
	v_pk_mul_f32 v[42:43], v[42:43], v[42:43]
	v_pk_mul_f32 v[40:41], v[40:41], v[40:41]
	s_mov_b32 s1, 0x280000
	v_cvt_pk_bf16_f32 v36, v40, v41
	v_cvt_pk_bf16_f32 v37, v42, v43
	v_cvt_pk_bf16_f32 v38, v38, v39
	v_cvt_pk_bf16_f32 v39, v44, v45
	global_store_dwordx4 v[52:53], v[36:39], off offset:256
	s_nop 0
	s_nop 0
	v_mov_b32_e32 v38, v250
	v_pk_mul_f32 v[32:33], v[32:33], v[38:39] op_sel_hi:[1,0]
	v_pk_mul_f32 v[30:31], v[30:31], v[38:39] op_sel_hi:[1,0]
	v_pk_mul_f32 v[28:29], v[28:29], v[38:39] op_sel_hi:[1,0]
	v_max_f32_e32 v33, 0, v33
	v_max_f32_e32 v32, 0, v32
	v_pk_mul_f32 v[34:35], v[34:35], v[38:39] op_sel_hi:[1,0]
	v_max_f32_e32 v29, 0, v29
	v_max_f32_e32 v28, 0, v28
	v_max_f32_e32 v31, 0, v31
	v_max_f32_e32 v30, 0, v30
	v_pk_mul_f32 v[32:33], v[32:33], v[32:33]
	v_max_f32_e32 v35, 0, v35
	v_max_f32_e32 v34, 0, v34
	v_pk_mul_f32 v[40:41], v[30:31], v[30:31]
	v_pk_mul_f32 v[30:31], v[28:29], v[28:29]
	v_cvt_pk_bf16_f32 v28, v32, v33
	v_add_co_u32_e32 v32, vcc, s1, v142
	v_pk_mul_f32 v[22:23], v[22:23], v[38:39] op_sel_hi:[1,0]
	v_pk_mul_f32 v[20:21], v[20:21], v[38:39] op_sel_hi:[1,0]
	v_pk_mul_f32 v[34:35], v[34:35], v[34:35]
	v_addc_co_u32_e32 v33, vcc, 0, v143, vcc
	v_cvt_pk_bf16_f32 v29, v34, v35
	v_pk_mul_f32 v[26:27], v[26:27], v[38:39] op_sel_hi:[1,0]
	v_pk_mul_f32 v[24:25], v[24:25], v[38:39] op_sel_hi:[1,0]
	v_max_f32_e32 v21, 0, v21
	v_max_f32_e32 v20, 0, v20
	v_max_f32_e32 v23, 0, v23
	v_max_f32_e32 v22, 0, v22
	v_lshl_add_u64 v[36:37], v[142:143], 0, s[4:5]
	v_cvt_pk_bf16_f32 v30, v30, v31
	v_cvt_pk_bf16_f32 v31, v40, v41
	global_store_dwordx4 v[32:33], v[28:31], off
	v_max_f32_e32 v25, 0, v25
	v_max_f32_e32 v24, 0, v24
	v_max_f32_e32 v27, 0, v27
	v_max_f32_e32 v26, 0, v26
	v_pk_mul_f32 v[28:29], v[22:23], v[22:23]
	v_pk_mul_f32 v[22:23], v[20:21], v[20:21]
	v_pk_mul_f32 v[26:27], v[26:27], v[26:27]
	v_pk_mul_f32 v[24:25], v[24:25], v[24:25]
	s_mov_b32 s1, 0x2c0000
	v_cvt_pk_bf16_f32 v20, v24, v25
	v_cvt_pk_bf16_f32 v21, v26, v27
	v_cvt_pk_bf16_f32 v22, v22, v23
	v_cvt_pk_bf16_f32 v23, v28, v29
	global_store_dwordx4 v[36:37], v[20:23], off offset:256
	s_nop 0
	s_mov_b64 s[4:5], 0x2c0000
	v_lshl_add_u64 v[22:23], v[142:143], 0, s[4:5]
	s_mov_b64 s[4:5], -1
	v_mov_b32_e32 v20, v251
	v_pk_mul_f32 v[16:17], v[16:17], v[20:21] op_sel_hi:[1,0]
	v_pk_mul_f32 v[14:15], v[14:15], v[20:21] op_sel_hi:[1,0]
	v_pk_mul_f32 v[12:13], v[12:13], v[20:21] op_sel_hi:[1,0]
	v_max_f32_e32 v17, 0, v17
	v_max_f32_e32 v16, 0, v16
	v_pk_mul_f32 v[18:19], v[18:19], v[20:21] op_sel_hi:[1,0]
	v_max_f32_e32 v13, 0, v13
	v_max_f32_e32 v12, 0, v12
	v_max_f32_e32 v15, 0, v15
	v_max_f32_e32 v14, 0, v14
	v_pk_mul_f32 v[16:17], v[16:17], v[16:17]
	v_max_f32_e32 v19, 0, v19
	v_max_f32_e32 v18, 0, v18
	v_pk_mul_f32 v[24:25], v[14:15], v[14:15]
	v_pk_mul_f32 v[14:15], v[12:13], v[12:13]
	v_cvt_pk_bf16_f32 v12, v16, v17
	v_add_co_u32_e32 v16, vcc, s1, v142
	v_pk_mul_f32 v[6:7], v[6:7], v[20:21] op_sel_hi:[1,0]
	v_pk_mul_f32 v[4:5], v[4:5], v[20:21] op_sel_hi:[1,0]
	v_pk_mul_f32 v[18:19], v[18:19], v[18:19]
	v_addc_co_u32_e32 v17, vcc, 0, v143, vcc
	v_cvt_pk_bf16_f32 v13, v18, v19
	v_pk_mul_f32 v[10:11], v[10:11], v[20:21] op_sel_hi:[1,0]
	v_pk_mul_f32 v[8:9], v[8:9], v[20:21] op_sel_hi:[1,0]
	v_max_f32_e32 v5, 0, v5
	v_max_f32_e32 v4, 0, v4
	v_max_f32_e32 v7, 0, v7
	v_max_f32_e32 v6, 0, v6
	v_cvt_pk_bf16_f32 v14, v14, v15
	v_cvt_pk_bf16_f32 v15, v24, v25
	global_store_dwordx4 v[16:17], v[12:15], off
	v_max_f32_e32 v9, 0, v9
	v_max_f32_e32 v8, 0, v8
	v_max_f32_e32 v11, 0, v11
	v_max_f32_e32 v10, 0, v10
	v_pk_mul_f32 v[12:13], v[6:7], v[6:7]
	v_pk_mul_f32 v[6:7], v[4:5], v[4:5]
	s_andn2_b64 vcc, exec, s[38:39]
	v_pk_mul_f32 v[10:11], v[10:11], v[10:11]
	v_pk_mul_f32 v[8:9], v[8:9], v[8:9]
	s_nop 0
	v_cvt_pk_bf16_f32 v4, v8, v9
	v_cvt_pk_bf16_f32 v5, v10, v11
	v_cvt_pk_bf16_f32 v6, v6, v7
	v_cvt_pk_bf16_f32 v7, v12, v13
	global_store_dwordx4 v[22:23], v[4:7], off offset:256
	s_cbranch_vccnz .LBB0_897
	s_andn2_b64 vcc, exec, s[2:3]
	s_cbranch_vccnz .LBB0_896
	s_barrier
	s_branch .LBB0_896

.LBB0_1183:
	s_ashr_i32 s59, s58, 31
	s_lshl_b64 s[10:11], s[58:59], 20
	s_add_u32 s60, s34, s10
	s_addc_u32 s61, s35, s11
	s_and_b64 s[10:11], s[40:41], exec
	s_cselect_b32 s1, s61, s5
	s_cselect_b32 s3, s60, s4
	s_ashr_i32 s57, s56, 31
	s_lshl_b64 s[10:11], s[56:57], 20
	s_add_u32 s62, s36, s10
	s_addc_u32 s63, s37, s11
	s_and_b64 s[10:11], s[40:41], exec
	s_cselect_b32 s7, s63, s9
	s_cselect_b32 s10, s62, s8
	s_add_u32 s4, s4, 0x80080
	s_addc_u32 s5, s5, 0
	s_add_u32 s11, s8, 0x100
	v_mov_b32_e32 v4, 0
	s_addc_u32 s21, s9, 0
	s_mov_b32 s22, -2
	v_mov_b32_e32 v5, v4
	v_mov_b32_e32 v6, v4
	v_mov_b32_e32 v7, v4
	v_mov_b32_e32 v8, v4
	v_mov_b32_e32 v9, v4
	v_mov_b32_e32 v10, v4
	v_mov_b32_e32 v11, v4
	v_mov_b32_e32 v20, v4
	v_mov_b32_e32 v21, v4
	v_mov_b32_e32 v22, v4
	v_mov_b32_e32 v23, v4
	v_mov_b32_e32 v24, v4
	v_mov_b32_e32 v25, v4
	v_mov_b32_e32 v26, v4
	v_mov_b32_e32 v27, v4
	v_mov_b32_e32 v36, v4
	v_mov_b32_e32 v37, v4
	v_mov_b32_e32 v38, v4
	v_mov_b32_e32 v39, v4
	v_mov_b32_e32 v40, v4
	v_mov_b32_e32 v41, v4
	v_mov_b32_e32 v42, v4
	v_mov_b32_e32 v43, v4
	v_mov_b32_e32 v52, v4
	v_mov_b32_e32 v53, v4
	v_mov_b32_e32 v54, v4
	v_mov_b32_e32 v55, v4
	v_mov_b32_e32 v56, v4
	v_mov_b32_e32 v57, v4
	v_mov_b32_e32 v58, v4
	v_mov_b32_e32 v59, v4
	v_mov_b32_e32 v12, v4
	v_mov_b32_e32 v13, v4
	v_mov_b32_e32 v14, v4
	v_mov_b32_e32 v15, v4
	v_mov_b32_e32 v16, v4
	v_mov_b32_e32 v17, v4
	v_mov_b32_e32 v18, v4
	v_mov_b32_e32 v19, v4
	v_mov_b32_e32 v28, v4
	v_mov_b32_e32 v29, v4
	v_mov_b32_e32 v30, v4
	v_mov_b32_e32 v31, v4
	v_mov_b32_e32 v32, v4
	v_mov_b32_e32 v33, v4
	v_mov_b32_e32 v34, v4
	v_mov_b32_e32 v35, v4
	v_mov_b32_e32 v44, v4
	v_mov_b32_e32 v45, v4
	v_mov_b32_e32 v46, v4
	v_mov_b32_e32 v47, v4
	v_mov_b32_e32 v48, v4
	v_mov_b32_e32 v49, v4
	v_mov_b32_e32 v50, v4
	v_mov_b32_e32 v51, v4
	v_mov_b32_e32 v60, v4
	v_mov_b32_e32 v61, v4
	v_mov_b32_e32 v62, v4
	v_mov_b32_e32 v63, v4
	v_mov_b32_e32 v64, v4
	v_mov_b32_e32 v65, v4
	v_mov_b32_e32 v66, v4
	v_mov_b32_e32 v67, v4
	v_mov_b32_e32 v68, v4
	v_mov_b32_e32 v69, v4
	v_mov_b32_e32 v70, v4
	v_mov_b32_e32 v71, v4
	v_mov_b32_e32 v72, v4
	v_mov_b32_e32 v73, v4
	v_mov_b32_e32 v74, v4
	v_mov_b32_e32 v75, v4
	v_mov_b32_e32 v84, v4
	v_mov_b32_e32 v85, v4
	v_mov_b32_e32 v86, v4
	v_mov_b32_e32 v87, v4
	v_mov_b32_e32 v88, v4
	v_mov_b32_e32 v89, v4
	v_mov_b32_e32 v90, v4
	v_mov_b32_e32 v91, v4
	v_mov_b32_e32 v100, v4
	v_mov_b32_e32 v101, v4
	v_mov_b32_e32 v102, v4
	v_mov_b32_e32 v103, v4
	v_mov_b32_e32 v104, v4
	v_mov_b32_e32 v105, v4
	v_mov_b32_e32 v106, v4
	v_mov_b32_e32 v107, v4
	v_mov_b32_e32 v116, v4
	v_mov_b32_e32 v117, v4
	v_mov_b32_e32 v118, v4
	v_mov_b32_e32 v119, v4
	v_mov_b32_e32 v120, v4
	v_mov_b32_e32 v121, v4
	v_mov_b32_e32 v122, v4
	v_mov_b32_e32 v123, v4
	v_mov_b32_e32 v76, v4
	v_mov_b32_e32 v77, v4
	v_mov_b32_e32 v78, v4
	v_mov_b32_e32 v79, v4
	v_mov_b32_e32 v80, v4
	v_mov_b32_e32 v81, v4
	v_mov_b32_e32 v82, v4
	v_mov_b32_e32 v83, v4
	v_mov_b32_e32 v92, v4
	v_mov_b32_e32 v93, v4
	v_mov_b32_e32 v94, v4
	v_mov_b32_e32 v95, v4
	v_mov_b32_e32 v96, v4
	v_mov_b32_e32 v97, v4
	v_mov_b32_e32 v98, v4
	v_mov_b32_e32 v99, v4
	v_mov_b32_e32 v108, v4
	v_mov_b32_e32 v109, v4
	v_mov_b32_e32 v110, v4
	v_mov_b32_e32 v111, v4
	v_mov_b32_e32 v112, v4
	v_mov_b32_e32 v113, v4
	v_mov_b32_e32 v114, v4
	v_mov_b32_e32 v115, v4
	v_mov_b32_e32 v124, v4
	v_mov_b32_e32 v125, v4
	v_mov_b32_e32 v126, v4
	v_mov_b32_e32 v127, v4
	v_mov_b32_e32 v128, v4
	v_mov_b32_e32 v129, v4
	v_mov_b32_e32 v130, v4
	v_mov_b32_e32 v131, v4
	v_lshl_add_u32 v148, s2, 8, v161
	v_ashrrev_i32_e32 v149, 31, v148
	v_lshl_add_u64 v[152:153], v[148:149], 2, s[50:51]
	global_load_dword v246, v[152:153], off
	global_load_dword v247, v[152:153], off offset:64
	global_load_dword v248, v[152:153], off offset:128
	global_load_dword v249, v[152:153], off offset:192
	global_load_dword v250, v[152:153], off offset:512
	global_load_dword v251, v[152:153], off offset:576
	global_load_dword v254, v[152:153], off offset:640
	global_load_dword v255, v[152:153], off offset:704

.LBB0_1187:
	s_lshl_b32 s1, s2, 8
	v_add_u32_e32 v148, s1, v161
	s_cmp_gt_i32 s46, 15
	s_mov_b64 s[4:5], -1
	v_ashrrev_i32_e32 v149, 31, v148
	s_cbranch_scc0 .LBB0_1189
	v_lshl_add_u64 v[152:153], v[148:149], 2, s[50:51]
	s_nop 0
	v_lshl_add_u32 v2, s46, 8, v164
	v_lshlrev_b64 v[150:151], 12, v[148:149]
	v_lshl_add_u64 v[150:151], s[52:53], 0, v[150:151]
	v_lshlrev_b64 v[154:155], 1, v[2:3]
	v_lshl_add_u64 v[150:151], v[150:151], 0, v[154:155]
	s_mov_b64 s[0:1], 0x80000
	s_mov_b64 s[4:5], 0
	v_mov_b32_e32 v166, v246
	v_pk_mul_f32 v[156:157], v[128:129], v[166:167] op_sel_hi:[1,0]
	v_pk_mul_f32 v[158:159], v[130:131], v[166:167] op_sel_hi:[1,0]
	v_cvt_pk_bf16_f32 v156, v156, v157
	v_pk_mul_f32 v[168:169], v[126:127], v[166:167] op_sel_hi:[1,0]
	v_cvt_pk_bf16_f32 v157, v158, v159
	v_pk_mul_f32 v[178:179], v[124:125], v[166:167] op_sel_hi:[1,0]
	s_nop 0
	v_cvt_pk_bf16_f32 v158, v178, v179
	v_cvt_pk_bf16_f32 v159, v168, v169
	global_store_dwordx4 v[150:151], v[156:159], off
	v_pk_mul_f32 v[168:169], v[118:119], v[166:167] op_sel_hi:[1,0]
	s_nop 0
	v_pk_mul_f32 v[156:157], v[120:121], v[166:167] op_sel_hi:[1,0]
	v_pk_mul_f32 v[158:159], v[122:123], v[166:167] op_sel_hi:[1,0]
	v_cvt_pk_bf16_f32 v156, v156, v157
	v_pk_mul_f32 v[166:167], v[116:117], v[166:167] op_sel_hi:[1,0]
	v_cvt_pk_bf16_f32 v157, v158, v159
	s_nop 0
	v_cvt_pk_bf16_f32 v158, v166, v167
	v_cvt_pk_bf16_f32 v159, v168, v169
	global_store_dwordx4 v[150:151], v[156:159], off offset:256
	s_nop 1
	v_or_b32_e32 v156, 16, v148
	v_ashrrev_i32_e32 v157, 31, v156
	v_lshl_add_u64 v[158:159], v[156:157], 2, s[50:51]
	s_nop 0
	v_lshlrev_b64 v[156:157], 12, v[156:157]
	v_lshl_add_u64 v[156:157], s[52:53], 0, v[156:157]
	v_lshl_add_u64 v[166:167], v[156:157], 0, v[154:155]
	v_mov_b32_e32 v2, v247
	v_pk_mul_f32 v[156:157], v[112:113], v[2:3] op_sel_hi:[1,0]
	v_pk_mul_f32 v[158:159], v[114:115], v[2:3] op_sel_hi:[1,0]
	v_cvt_pk_bf16_f32 v156, v156, v157
	v_pk_mul_f32 v[168:169], v[110:111], v[2:3] op_sel_hi:[1,0]
	v_cvt_pk_bf16_f32 v157, v158, v159
	v_pk_mul_f32 v[178:179], v[108:109], v[2:3] op_sel_hi:[1,0]
	s_nop 0
	v_cvt_pk_bf16_f32 v158, v178, v179
	v_cvt_pk_bf16_f32 v159, v168, v169
	global_store_dwordx4 v[166:167], v[156:159], off
	v_pk_mul_f32 v[168:169], v[102:103], v[2:3] op_sel_hi:[1,0]
	v_pk_mul_f32 v[178:179], v[100:101], v[2:3] op_sel_hi:[1,0]
	v_pk_mul_f32 v[156:157], v[104:105], v[2:3] op_sel_hi:[1,0]
	v_pk_mul_f32 v[158:159], v[106:107], v[2:3] op_sel_hi:[1,0]
	v_cvt_pk_bf16_f32 v156, v156, v157
	s_nop 0
	v_cvt_pk_bf16_f32 v157, v158, v159
	v_cvt_pk_bf16_f32 v158, v178, v179
	v_cvt_pk_bf16_f32 v159, v168, v169
	global_store_dwordx4 v[166:167], v[156:159], off offset:256
	s_nop 1
	v_or_b32_e32 v156, 32, v148
	v_ashrrev_i32_e32 v157, 31, v156
	v_lshl_add_u64 v[158:159], v[156:157], 2, s[50:51]
	s_nop 0
	v_lshlrev_b64 v[156:157], 12, v[156:157]
	v_lshl_add_u64 v[156:157], s[52:53], 0, v[156:157]
	v_lshl_add_u64 v[166:167], v[156:157], 0, v[154:155]
	v_mov_b32_e32 v2, v248
	v_pk_mul_f32 v[156:157], v[96:97], v[2:3] op_sel_hi:[1,0]
	v_pk_mul_f32 v[158:159], v[98:99], v[2:3] op_sel_hi:[1,0]
	v_cvt_pk_bf16_f32 v156, v156, v157
	v_pk_mul_f32 v[168:169], v[94:95], v[2:3] op_sel_hi:[1,0]
	v_cvt_pk_bf16_f32 v157, v158, v159
	v_pk_mul_f32 v[178:179], v[92:93], v[2:3] op_sel_hi:[1,0]
	s_nop 0
	v_cvt_pk_bf16_f32 v158, v178, v179
	v_cvt_pk_bf16_f32 v159, v168, v169
	global_store_dwordx4 v[166:167], v[156:159], off
	v_pk_mul_f32 v[168:169], v[86:87], v[2:3] op_sel_hi:[1,0]
	v_pk_mul_f32 v[178:179], v[84:85], v[2:3] op_sel_hi:[1,0]
	v_pk_mul_f32 v[156:157], v[88:89], v[2:3] op_sel_hi:[1,0]
	v_pk_mul_f32 v[158:159], v[90:91], v[2:3] op_sel_hi:[1,0]
	v_cvt_pk_bf16_f32 v156, v156, v157
	s_nop 0
	v_cvt_pk_bf16_f32 v157, v158, v159
	v_cvt_pk_bf16_f32 v158, v178, v179
	v_cvt_pk_bf16_f32 v159, v168, v169
	global_store_dwordx4 v[166:167], v[156:159], off offset:256
	s_nop 1
	v_or_b32_e32 v156, 48, v148
	v_ashrrev_i32_e32 v157, 31, v156
	v_lshl_add_u64 v[158:159], v[156:157], 2, s[50:51]
	s_nop 0
	v_lshlrev_b64 v[156:157], 12, v[156:157]
	v_lshl_add_u64 v[156:157], s[52:53], 0, v[156:157]
	v_lshl_add_u64 v[158:159], v[156:157], 0, v[154:155]
	v_mov_b32_e32 v2, v249
	v_pk_mul_f32 v[156:157], v[82:83], v[2:3] op_sel_hi:[1,0]
	v_pk_mul_f32 v[154:155], v[80:81], v[2:3] op_sel_hi:[1,0]
	v_pk_mul_f32 v[166:167], v[78:79], v[2:3] op_sel_hi:[1,0]
	v_pk_mul_f32 v[168:169], v[76:77], v[2:3] op_sel_hi:[1,0]
	v_cvt_pk_bf16_f32 v154, v154, v155
	v_cvt_pk_bf16_f32 v155, v156, v157
	s_nop 0
	v_cvt_pk_bf16_f32 v156, v168, v169
	v_cvt_pk_bf16_f32 v157, v166, v167
	global_store_dwordx4 v[158:159], v[154:157], off
	v_pk_mul_f32 v[166:167], v[70:71], v[2:3] op_sel_hi:[1,0]
	v_pk_mul_f32 v[168:169], v[68:69], v[2:3] op_sel_hi:[1,0]
	v_pk_mul_f32 v[156:157], v[74:75], v[2:3] op_sel_hi:[1,0]
	v_pk_mul_f32 v[154:155], v[72:73], v[2:3] op_sel_hi:[1,0]
	s_nop 0
	v_cvt_pk_bf16_f32 v154, v154, v155
	v_cvt_pk_bf16_f32 v155, v156, v157
	v_cvt_pk_bf16_f32 v156, v168, v169
	v_cvt_pk_bf16_f32 v157, v166, v167
	global_store_dwordx4 v[158:159], v[154:157], off offset:256
	s_nop 0
	v_lshl_add_u64 v[158:159], v[150:151], 0, s[0:1]
	s_mov_b32 s0, 0x80000
	v_mov_b32_e32 v2, v250
	v_pk_mul_f32 v[156:157], v[66:67], v[2:3] op_sel_hi:[1,0]
	v_pk_mul_f32 v[154:155], v[64:65], v[2:3] op_sel_hi:[1,0]
	v_pk_mul_f32 v[166:167], v[62:63], v[2:3] op_sel_hi:[1,0]
	v_pk_mul_f32 v[168:169], v[60:61], v[2:3] op_sel_hi:[1,0]
	v_cvt_pk_bf16_f32 v154, v154, v155
	v_cvt_pk_bf16_f32 v155, v156, v157
	s_nop 0
	v_cvt_pk_bf16_f32 v156, v168, v169
	v_cvt_pk_bf16_f32 v157, v166, v167
	v_add_co_u32_e32 v166, vcc, s0, v150
	v_pk_mul_f32 v[168:169], v[52:53], v[2:3] op_sel_hi:[1,0]
	s_nop 0
	v_addc_co_u32_e32 v167, vcc, 0, v151, vcc
	global_store_dwordx4 v[166:167], v[154:157], off
	v_pk_mul_f32 v[166:167], v[54:55], v[2:3] op_sel_hi:[1,0]
	s_mov_b64 s[0:1], 0x90000
	v_pk_mul_f32 v[156:157], v[58:59], v[2:3] op_sel_hi:[1,0]
	v_pk_mul_f32 v[154:155], v[56:57], v[2:3] op_sel_hi:[1,0]
	s_nop 0
	v_cvt_pk_bf16_f32 v154, v154, v155
	v_cvt_pk_bf16_f32 v155, v156, v157
	v_cvt_pk_bf16_f32 v156, v168, v169
	v_cvt_pk_bf16_f32 v157, v166, v167
	global_store_dwordx4 v[158:159], v[154:157], off offset:256
	s_nop 0
	v_lshl_add_u64 v[158:159], v[150:151], 0, s[0:1]
	s_mov_b32 s0, 0x90000
	v_mov_b32_e32 v2, v251
	v_pk_mul_f32 v[156:157], v[50:51], v[2:3] op_sel_hi:[1,0]
	v_pk_mul_f32 v[154:155], v[48:49], v[2:3] op_sel_hi:[1,0]
	v_pk_mul_f32 v[166:167], v[46:47], v[2:3] op_sel_hi:[1,0]
	v_pk_mul_f32 v[168:169], v[44:45], v[2:3] op_sel_hi:[1,0]
	v_cvt_pk_bf16_f32 v154, v154, v155
	v_cvt_pk_bf16_f32 v155, v156, v157
	s_nop 0
	v_cvt_pk_bf16_f32 v156, v168, v169
	v_cvt_pk_bf16_f32 v157, v166, v167
	v_add_co_u32_e32 v166, vcc, s0, v150
	v_pk_mul_f32 v[168:169], v[36:37], v[2:3] op_sel_hi:[1,0]
	s_nop 0
	v_addc_co_u32_e32 v167, vcc, 0, v151, vcc
	global_store_dwordx4 v[166:167], v[154:157], off
	v_pk_mul_f32 v[166:167], v[38:39], v[2:3] op_sel_hi:[1,0]
	s_mov_b64 s[0:1], 0xa0000
	v_pk_mul_f32 v[156:157], v[42:43], v[2:3] op_sel_hi:[1,0]
	v_pk_mul_f32 v[154:155], v[40:41], v[2:3] op_sel_hi:[1,0]
	s_nop 0
	v_cvt_pk_bf16_f32 v154, v154, v155
	v_cvt_pk_bf16_f32 v155, v156, v157
	v_cvt_pk_bf16_f32 v156, v168, v169
	v_cvt_pk_bf16_f32 v157, v166, v167
	global_store_dwordx4 v[158:159], v[154:157], off offset:256
	s_nop 0
	v_lshl_add_u64 v[158:159], v[150:151], 0, s[0:1]
	s_mov_b32 s0, 0xa0000
	v_mov_b32_e32 v2, v254
	v_pk_mul_f32 v[156:157], v[34:35], v[2:3] op_sel_hi:[1,0]
	v_pk_mul_f32 v[154:155], v[32:33], v[2:3] op_sel_hi:[1,0]
	v_pk_mul_f32 v[166:167], v[30:31], v[2:3] op_sel_hi:[1,0]
	v_pk_mul_f32 v[168:169], v[28:29], v[2:3] op_sel_hi:[1,0]
	v_cvt_pk_bf16_f32 v154, v154, v155
	v_cvt_pk_bf16_f32 v155, v156, v157
	s_nop 0
	v_cvt_pk_bf16_f32 v156, v168, v169
	v_cvt_pk_bf16_f32 v157, v166, v167
	v_add_co_u32_e32 v166, vcc, s0, v150
	v_pk_mul_f32 v[168:169], v[20:21], v[2:3] op_sel_hi:[1,0]
	s_nop 0
	v_addc_co_u32_e32 v167, vcc, 0, v151, vcc
	global_store_dwordx4 v[166:167], v[154:157], off
	v_pk_mul_f32 v[166:167], v[22:23], v[2:3] op_sel_hi:[1,0]
	s_mov_b64 s[0:1], 0xb0000
	v_pk_mul_f32 v[156:157], v[26:27], v[2:3] op_sel_hi:[1,0]
	v_pk_mul_f32 v[154:155], v[24:25], v[2:3] op_sel_hi:[1,0]
	s_nop 0
	v_cvt_pk_bf16_f32 v154, v154, v155
	v_cvt_pk_bf16_f32 v155, v156, v157
	v_cvt_pk_bf16_f32 v156, v168, v169
	v_cvt_pk_bf16_f32 v157, v166, v167
	global_store_dwordx4 v[158:159], v[154:157], off offset:256
	s_nop 0
	v_mov_b32_e32 v2, v255
	v_pk_mul_f32 v[152:153], v[16:17], v[2:3] op_sel_hi:[1,0]
	v_lshl_add_u64 v[156:157], v[150:151], 0, s[0:1]
	s_mov_b32 s0, 0xb0000
	v_add_co_u32_e32 v150, vcc, s0, v150
	v_pk_mul_f32 v[154:155], v[18:19], v[2:3] op_sel_hi:[1,0]
	v_cvt_pk_bf16_f32 v152, v152, v153
	s_nop 0
	v_addc_co_u32_e32 v151, vcc, 0, v151, vcc
	v_cvt_pk_bf16_f32 v153, v154, v155
	v_pk_mul_f32 v[158:159], v[14:15], v[2:3] op_sel_hi:[1,0]
	v_pk_mul_f32 v[166:167], v[12:13], v[2:3] op_sel_hi:[1,0]
	s_nop 0
	v_cvt_pk_bf16_f32 v154, v166, v167
	v_cvt_pk_bf16_f32 v155, v158, v159
	global_store_dwordx4 v[150:151], v[152:155], off
	v_pk_mul_f32 v[150:151], v[8:9], v[2:3] op_sel_hi:[1,0]
	v_pk_mul_f32 v[158:159], v[4:5], v[2:3] op_sel_hi:[1,0]
	v_pk_mul_f32 v[152:153], v[10:11], v[2:3] op_sel_hi:[1,0]
	v_pk_mul_f32 v[154:155], v[6:7], v[2:3] op_sel_hi:[1,0]
	v_cvt_pk_bf16_f32 v150, v150, v151
	v_cvt_pk_bf16_f32 v151, v152, v153
	v_cvt_pk_bf16_f32 v152, v158, v159
	s_nop 0
	v_cvt_pk_bf16_f32 v153, v154, v155
	global_store_dwordx4 v[156:157], v[150:153], off offset:256
.LBB0_1189:
	s_andn2_b64 vcc, exec, s[4:5]
	s_movk_i32 s33, 0x7ff
	s_cbranch_vccnz .LBB0_1265
	v_lshl_add_u64 v[150:151], v[148:149], 2, s[50:51]
	s_nop 0
	s_cmp_lt_i32 s46, 8
	s_cselect_b64 s[4:5], -1, 0
	s_cmp_lt_i32 s2, 64
	s_cselect_b64 s[12:13], -1, 0
	s_cmp_gt_i32 s2, 63
	s_cselect_b64 s[8:9], -1, 0
	s_mov_b64 s[26:27], -1
	s_and_b64 vcc, exec, s[8:9]
	s_cbranch_vccz .LBB0_1192
	s_and_b64 s[10:11], s[4:5], exec
	v_readlane_b32 s0, v252, 1
	v_readlane_b32 s1, v252, 5
	v_add_u32_e32 v156, 0xffffc000, v148
	s_cselect_b32 s11, s0, s1
	v_readlane_b32 s0, v252, 0
	v_readlane_b32 s1, v252, 2
	s_cselect_b32 s10, s0, s1
	v_ashrrev_i32_e32 v157, 31, v156
	v_ashrrev_i32_e32 v1, 5, v156
	s_movk_i32 s0, 0x480
	v_lshlrev_b64 v[152:153], 13, v[156:157]
	v_mad_i64_i32 v[156:157], s[26:27], v1, s0, v[140:141]
	v_lshl_add_u64 v[152:153], s[10:11], 0, v[152:153]
	s_cselect_b32 s11, s74, s76
	s_cselect_b32 s10, s73, s75
	v_lshlrev_b64 v[156:157], 12, v[156:157]
	v_lshl_add_u64 v[156:157], s[10:11], 0, v[156:157]
	s_mov_b64 s[26:27], 0

.LBB0_1194:
	s_lshl_b32 s1, s46, 8
	s_and_b32 s1, s1, 0x700
	v_or_b32_e32 v1, s1, v163
	s_and_b64 s[10:11], s[4:5], s[12:13]
	v_lshlrev_b32_e32 v2, 2, v1
	v_lshl_add_u64 v[158:159], v[152:153], 0, v[2:3]
	v_lshlrev_b32_e32 v152, 1, v1
	v_mov_b32_e32 v153, v3
	v_cndmask_b32_e64 v1, 0, 1, s[10:11]
	v_lshl_add_u64 v[156:157], v[156:157], 0, v[152:153]
	v_mov_b32_e32 v154, v246
	v_pk_mul_f32 v[130:131], v[130:131], v[154:155] op_sel_hi:[1,0]
	v_pk_mul_f32 v[128:129], v[128:129], v[154:155] op_sel_hi:[1,0]
	v_pk_mul_f32 v[126:127], v[126:127], v[154:155] op_sel_hi:[1,0]
	v_pk_mul_f32 v[124:125], v[124:125], v[154:155] op_sel_hi:[1,0]
	v_cmp_ne_u32_e64 s[42:43], 1, v1
	s_andn2_b64 vcc, exec, s[10:11]
	global_store_dwordx4 v[158:159], v[128:131], off
	global_store_dwordx4 v[158:159], v[124:127], off offset:16
	v_cvt_pk_bf16_f32 v166, v128, v129
	v_cvt_pk_bf16_f32 v167, v130, v131
	v_cvt_pk_bf16_f32 v168, v124, v125
	v_cvt_pk_bf16_f32 v169, v126, v127
	global_store_dwordx4 v[156:157], v[166:169], off
	s_cbranch_vccnz .LBB0_1196
	v_pk_mul_f32 v[130:131], v[130:131], v[130:131]
	v_pk_mul_f32 v[128:129], v[128:129], v[128:129]
	v_pk_mul_f32 v[126:127], v[126:127], v[126:127]
	v_pk_mul_f32 v[124:125], v[124:125], v[124:125]
	v_pk_mov_b32 v[166:167], v[128:129], v[130:131] op_sel:[1,0]
	v_mov_b32_e32 v129, v131
	v_pk_add_f32 v[128:129], v[166:167], v[128:129]
	v_mov_b32_e32 v130, v126
	v_mov_b32_e32 v131, v124
	v_mov_b32_e32 v124, v127
	v_pk_add_f32 v[124:125], v[130:131], v[124:125]
	v_add_f32_e32 v1, v128, v129
	v_add_f32_e32 v1, v125, v1
	v_add_f32_e32 v1, v124, v1
	v_max_f32_e32 v124, 0, v1
	s_branch .LBB0_1197

.LBB0_1199:
	v_or_b32_e32 v118, 16, v148
	v_ashrrev_i32_e32 v119, 31, v118
	v_lshl_add_u64 v[116:117], v[118:119], 2, s[50:51]
	s_nop 0
	v_cndmask_b32_e64 v117, 0, 1, s[8:9]
	v_cmp_ne_u32_e64 s[44:45], 1, v117
	s_andn2_b64 vcc, exec, s[8:9]
	s_mov_b64 s[8:9], -1
	s_cbranch_vccnz .LBB0_1201
	s_and_b64 s[8:9], s[4:5], exec
	v_readlane_b32 s0, v252, 1
	v_readlane_b32 s1, v252, 5
	v_add_u32_e32 v122, 0xffffc010, v148
	s_cselect_b32 s9, s0, s1
	v_readlane_b32 s0, v252, 0
	v_readlane_b32 s1, v252, 2
	s_cselect_b32 s8, s0, s1
	v_ashrrev_i32_e32 v123, 31, v122
	v_ashrrev_i32_e32 v117, 5, v122
	s_movk_i32 s0, 0x480
	v_lshlrev_b64 v[120:121], 13, v[122:123]
	v_mad_i64_i32 v[122:123], s[10:11], v117, s0, v[142:143]
	v_lshl_add_u64 v[120:121], s[8:9], 0, v[120:121]
	s_cselect_b32 s9, s74, s76
	s_cselect_b32 s8, s73, s75
	v_lshlrev_b64 v[122:123], 12, v[122:123]
	v_lshl_add_u64 v[122:123], s[8:9], 0, v[122:123]
	s_mov_b64 s[8:9], 0

.LBB0_1203:
	v_mov_b32_e32 v153, v3
	v_lshl_add_u64 v[120:121], v[120:121], 0, v[2:3]
	v_lshl_add_u64 v[118:119], v[122:123], 0, v[152:153]
	v_mov_b32_e32 v116, v247
	v_pk_mul_f32 v[114:115], v[114:115], v[116:117] op_sel_hi:[1,0]
	v_pk_mul_f32 v[112:113], v[112:113], v[116:117] op_sel_hi:[1,0]
	v_pk_mul_f32 v[110:111], v[110:111], v[116:117] op_sel_hi:[1,0]
	v_pk_mul_f32 v[108:109], v[108:109], v[116:117] op_sel_hi:[1,0]
	s_and_b64 vcc, exec, s[42:43]
	global_store_dwordx4 v[120:121], v[112:115], off
	global_store_dwordx4 v[120:121], v[108:111], off offset:16
	v_cvt_pk_bf16_f32 v126, v112, v113
	v_cvt_pk_bf16_f32 v127, v114, v115
	v_cvt_pk_bf16_f32 v128, v108, v109
	v_cvt_pk_bf16_f32 v129, v110, v111
	global_store_dwordx4 v[118:119], v[126:129], off
	s_cbranch_vccnz .LBB0_1205
	v_pk_mul_f32 v[114:115], v[114:115], v[114:115]
	v_pk_mul_f32 v[112:113], v[112:113], v[112:113]
	v_pk_mul_f32 v[110:111], v[110:111], v[110:111]
	v_pk_mul_f32 v[108:109], v[108:109], v[108:109]
	v_pk_mov_b32 v[122:123], v[112:113], v[114:115] op_sel:[1,0]
	v_mov_b32_e32 v113, v115
	v_pk_add_f32 v[112:113], v[122:123], v[112:113]
	v_mov_b32_e32 v114, v110
	v_mov_b32_e32 v115, v108
	v_mov_b32_e32 v108, v111
	v_pk_add_f32 v[108:109], v[114:115], v[108:109]
	v_add_f32_e32 v110, v112, v113
	v_add_f32_e32 v109, v109, v110
	v_add_f32_e32 v108, v108, v109
	v_max_f32_e32 v109, v124, v124
	v_max_f32_e32 v124, v109, v108

.LBB0_1207:
	v_or_b32_e32 v102, 32, v148
	v_ashrrev_i32_e32 v103, 31, v102
	v_lshl_add_u64 v[100:101], v[102:103], 2, s[50:51]
	s_nop 0
	s_and_b64 vcc, exec, s[44:45]
	s_mov_b64 s[8:9], -1
	s_cbranch_vccnz .LBB0_1209
	s_and_b64 s[8:9], s[4:5], exec
	v_readlane_b32 s0, v252, 1
	v_readlane_b32 s1, v252, 5
	v_add_u32_e32 v106, 0xffffc020, v148
	s_cselect_b32 s9, s0, s1
	v_readlane_b32 s0, v252, 0
	v_readlane_b32 s1, v252, 2
	s_cselect_b32 s8, s0, s1
	v_ashrrev_i32_e32 v107, 31, v106
	v_ashrrev_i32_e32 v101, 5, v106
	s_movk_i32 s0, 0x480
	v_lshlrev_b64 v[104:105], 13, v[106:107]
	v_mad_i64_i32 v[106:107], s[10:11], v101, s0, v[140:141]
	v_lshl_add_u64 v[104:105], s[8:9], 0, v[104:105]
	s_cselect_b32 s9, s74, s76
	s_cselect_b32 s8, s73, s75
	v_lshlrev_b64 v[106:107], 12, v[106:107]
	v_lshl_add_u64 v[106:107], s[8:9], 0, v[106:107]
	s_mov_b64 s[8:9], 0

.LBB0_1211:
	v_mov_b32_e32 v153, v3
	v_lshl_add_u64 v[104:105], v[104:105], 0, v[2:3]
	v_lshl_add_u64 v[102:103], v[106:107], 0, v[152:153]
	v_mov_b32_e32 v100, v248
	v_pk_mul_f32 v[98:99], v[98:99], v[100:101] op_sel_hi:[1,0]
	v_pk_mul_f32 v[96:97], v[96:97], v[100:101] op_sel_hi:[1,0]
	v_pk_mul_f32 v[94:95], v[94:95], v[100:101] op_sel_hi:[1,0]
	v_pk_mul_f32 v[92:93], v[92:93], v[100:101] op_sel_hi:[1,0]
	s_and_b64 vcc, exec, s[42:43]
	global_store_dwordx4 v[104:105], v[96:99], off
	global_store_dwordx4 v[104:105], v[92:95], off offset:16
	v_cvt_pk_bf16_f32 v106, v96, v97
	v_cvt_pk_bf16_f32 v107, v98, v99
	v_cvt_pk_bf16_f32 v108, v92, v93
	v_cvt_pk_bf16_f32 v109, v94, v95
	global_store_dwordx4 v[102:103], v[106:109], off
	s_cbranch_vccnz .LBB0_1213
	v_pk_mul_f32 v[98:99], v[98:99], v[98:99]
	v_pk_mul_f32 v[96:97], v[96:97], v[96:97]
	v_pk_mul_f32 v[94:95], v[94:95], v[94:95]
	v_pk_mul_f32 v[92:93], v[92:93], v[92:93]
	v_pk_mov_b32 v[106:107], v[96:97], v[98:99] op_sel:[1,0]
	v_mov_b32_e32 v97, v99
	v_pk_add_f32 v[96:97], v[106:107], v[96:97]
	v_mov_b32_e32 v98, v94
	v_mov_b32_e32 v99, v92
	v_mov_b32_e32 v92, v95
	v_pk_add_f32 v[92:93], v[98:99], v[92:93]
	v_add_f32_e32 v94, v96, v97
	v_add_f32_e32 v93, v93, v94
	v_add_f32_e32 v92, v92, v93
	v_max_f32_e32 v93, v124, v124
	v_max_f32_e32 v124, v93, v92

.LBB0_1215:
	v_or_b32_e32 v86, 48, v148
	v_ashrrev_i32_e32 v87, 31, v86
	v_lshl_add_u64 v[84:85], v[86:87], 2, s[50:51]
	s_nop 0
	s_and_b64 vcc, exec, s[44:45]
	s_mov_b64 s[8:9], -1
	s_cbranch_vccnz .LBB0_1217
	s_and_b64 s[8:9], s[4:5], exec
	v_readlane_b32 s0, v252, 1
	v_readlane_b32 s1, v252, 5
	v_add_u32_e32 v90, 0xffffc030, v148
	s_cselect_b32 s9, s0, s1
	v_readlane_b32 s0, v252, 0
	v_readlane_b32 s1, v252, 2
	s_cselect_b32 s8, s0, s1
	v_ashrrev_i32_e32 v91, 31, v90
	v_ashrrev_i32_e32 v85, 5, v90
	s_movk_i32 s0, 0x480
	v_lshlrev_b64 v[88:89], 13, v[90:91]
	v_mad_i64_i32 v[90:91], s[10:11], v85, s0, v[142:143]
	v_lshl_add_u64 v[88:89], s[8:9], 0, v[88:89]
	s_cselect_b32 s9, s74, s76
	s_cselect_b32 s8, s73, s75
	v_lshlrev_b64 v[90:91], 12, v[90:91]
	v_lshl_add_u64 v[90:91], s[8:9], 0, v[90:91]
	s_mov_b64 s[8:9], 0

.LBB0_1219:
	v_mov_b32_e32 v153, v3
	v_lshl_add_u64 v[88:89], v[88:89], 0, v[2:3]
	v_lshl_add_u64 v[86:87], v[90:91], 0, v[152:153]
	v_mov_b32_e32 v84, v249
	v_pk_mul_f32 v[82:83], v[82:83], v[84:85] op_sel_hi:[1,0]
	v_pk_mul_f32 v[80:81], v[80:81], v[84:85] op_sel_hi:[1,0]
	v_pk_mul_f32 v[78:79], v[78:79], v[84:85] op_sel_hi:[1,0]
	v_pk_mul_f32 v[76:77], v[76:77], v[84:85] op_sel_hi:[1,0]
	s_and_b64 vcc, exec, s[42:43]
	global_store_dwordx4 v[88:89], v[80:83], off
	global_store_dwordx4 v[88:89], v[76:79], off offset:16
	v_cvt_pk_bf16_f32 v90, v80, v81
	v_cvt_pk_bf16_f32 v91, v82, v83
	v_cvt_pk_bf16_f32 v92, v76, v77
	v_cvt_pk_bf16_f32 v93, v78, v79
	global_store_dwordx4 v[86:87], v[90:93], off
	s_cbranch_vccnz .LBB0_1221
	v_pk_mul_f32 v[82:83], v[82:83], v[82:83]
	v_pk_mul_f32 v[80:81], v[80:81], v[80:81]
	v_pk_mul_f32 v[78:79], v[78:79], v[78:79]
	v_pk_mul_f32 v[76:77], v[76:77], v[76:77]
	v_pk_mov_b32 v[90:91], v[80:81], v[82:83] op_sel:[1,0]
	v_mov_b32_e32 v81, v83
	v_pk_add_f32 v[80:81], v[90:91], v[80:81]
	v_mov_b32_e32 v82, v78
	v_mov_b32_e32 v83, v76
	v_mov_b32_e32 v76, v79
	v_pk_add_f32 v[76:77], v[82:83], v[76:77]
	v_add_f32_e32 v78, v80, v81
	v_add_f32_e32 v77, v77, v78
	v_add_f32_e32 v76, v76, v77
	v_max_f32_e32 v77, v124, v124
	v_max_f32_e32 v124, v77, v76

.LBB0_1223:
	s_nop 0
	s_and_b64 vcc, exec, s[44:45]
	s_mov_b64 s[8:9], -1
	s_cbranch_vccnz .LBB0_1225
	s_and_b64 s[8:9], s[4:5], exec
	v_readlane_b32 s0, v252, 1
	v_readlane_b32 s1, v252, 5
	v_add_u32_e32 v72, 0xffffc080, v148
	s_cselect_b32 s9, s0, s1
	v_readlane_b32 s0, v252, 0
	v_readlane_b32 s1, v252, 2
	s_cselect_b32 s8, s0, s1
	v_ashrrev_i32_e32 v73, 31, v72
	v_ashrrev_i32_e32 v69, 5, v72
	s_movk_i32 s0, 0x480
	v_lshlrev_b64 v[70:71], 13, v[72:73]
	v_mad_i64_i32 v[72:73], s[10:11], v69, s0, v[140:141]
	v_lshl_add_u64 v[70:71], s[8:9], 0, v[70:71]
	s_cselect_b32 s9, s74, s76
	s_cselect_b32 s8, s73, s75
	v_lshlrev_b64 v[72:73], 12, v[72:73]
	v_lshl_add_u64 v[74:75], s[8:9], 0, v[72:73]
	s_cbranch_execz .LBB0_1226
	s_branch .LBB0_1227

.LBB0_1227:
	v_mov_b32_e32 v153, v3
	v_lshl_add_u64 v[72:73], v[70:71], 0, v[2:3]
	v_lshl_add_u64 v[70:71], v[74:75], 0, v[152:153]
	v_mov_b32_e32 v68, v250
	v_pk_mul_f32 v[66:67], v[66:67], v[68:69] op_sel_hi:[1,0]
	v_pk_mul_f32 v[64:65], v[64:65], v[68:69] op_sel_hi:[1,0]
	v_pk_mul_f32 v[62:63], v[62:63], v[68:69] op_sel_hi:[1,0]
	v_pk_mul_f32 v[60:61], v[60:61], v[68:69] op_sel_hi:[1,0]
	s_and_b64 vcc, exec, s[42:43]
	global_store_dwordx4 v[72:73], v[64:67], off
	global_store_dwordx4 v[72:73], v[60:63], off offset:16
	v_cvt_pk_bf16_f32 v74, v64, v65
	v_cvt_pk_bf16_f32 v75, v66, v67
	v_cvt_pk_bf16_f32 v76, v60, v61
	v_cvt_pk_bf16_f32 v77, v62, v63
	global_store_dwordx4 v[70:71], v[74:77], off
	s_cbranch_vccnz .LBB0_1229
	v_pk_mul_f32 v[66:67], v[66:67], v[66:67]
	v_pk_mul_f32 v[64:65], v[64:65], v[64:65]
	v_pk_mul_f32 v[62:63], v[62:63], v[62:63]
	v_pk_mul_f32 v[60:61], v[60:61], v[60:61]
	v_pk_mov_b32 v[74:75], v[64:65], v[66:67] op_sel:[1,0]
	v_mov_b32_e32 v65, v67
	v_pk_add_f32 v[64:65], v[74:75], v[64:65]
	v_mov_b32_e32 v66, v62
	v_mov_b32_e32 v67, v60
	v_mov_b32_e32 v60, v63
	v_pk_add_f32 v[60:61], v[66:67], v[60:61]
	v_add_f32_e32 v62, v64, v65
	v_add_f32_e32 v61, v61, v62
	v_add_f32_e32 v60, v60, v61
	v_max_f32_e32 v61, v124, v124
	v_max_f32_e32 v124, v61, v60

.LBB0_1231:
	s_nop 0
	s_and_b64 vcc, exec, s[44:45]
	s_mov_b64 s[8:9], -1
	s_cbranch_vccnz .LBB0_1233
	s_and_b64 s[8:9], s[4:5], exec
	v_readlane_b32 s0, v252, 1
	v_readlane_b32 s1, v252, 5
	v_add_u32_e32 v56, 0xffffc090, v148
	s_cselect_b32 s9, s0, s1
	v_readlane_b32 s0, v252, 0
	v_readlane_b32 s1, v252, 2
	s_cselect_b32 s8, s0, s1
	v_ashrrev_i32_e32 v57, 31, v56
	v_ashrrev_i32_e32 v53, 5, v56
	s_movk_i32 s0, 0x480
	v_lshlrev_b64 v[54:55], 13, v[56:57]
	v_mad_i64_i32 v[56:57], s[10:11], v53, s0, v[142:143]
	v_lshl_add_u64 v[54:55], s[8:9], 0, v[54:55]
	s_cselect_b32 s9, s74, s76
	s_cselect_b32 s8, s73, s75
	v_lshlrev_b64 v[56:57], 12, v[56:57]
	v_lshl_add_u64 v[58:59], s[8:9], 0, v[56:57]
	s_cbranch_execz .LBB0_1234
	s_branch .LBB0_1235

.LBB0_1235:
	v_mov_b32_e32 v153, v3
	v_lshl_add_u64 v[56:57], v[54:55], 0, v[2:3]
	v_lshl_add_u64 v[54:55], v[58:59], 0, v[152:153]
	v_mov_b32_e32 v52, v251
	v_pk_mul_f32 v[50:51], v[50:51], v[52:53] op_sel_hi:[1,0]
	v_pk_mul_f32 v[48:49], v[48:49], v[52:53] op_sel_hi:[1,0]
	v_pk_mul_f32 v[46:47], v[46:47], v[52:53] op_sel_hi:[1,0]
	v_pk_mul_f32 v[44:45], v[44:45], v[52:53] op_sel_hi:[1,0]
	s_and_b64 vcc, exec, s[42:43]
	global_store_dwordx4 v[56:57], v[48:51], off
	global_store_dwordx4 v[56:57], v[44:47], off offset:16
	v_cvt_pk_bf16_f32 v58, v48, v49
	v_cvt_pk_bf16_f32 v59, v50, v51
	v_cvt_pk_bf16_f32 v60, v44, v45
	v_cvt_pk_bf16_f32 v61, v46, v47
	global_store_dwordx4 v[54:55], v[58:61], off
	s_cbranch_vccnz .LBB0_1237
	v_pk_mul_f32 v[50:51], v[50:51], v[50:51]
	v_pk_mul_f32 v[48:49], v[48:49], v[48:49]
	v_pk_mul_f32 v[46:47], v[46:47], v[46:47]
	v_pk_mul_f32 v[44:45], v[44:45], v[44:45]
	v_pk_mov_b32 v[58:59], v[48:49], v[50:51] op_sel:[1,0]
	v_mov_b32_e32 v49, v51
	v_pk_add_f32 v[48:49], v[58:59], v[48:49]
	v_mov_b32_e32 v50, v46
	v_mov_b32_e32 v51, v44
	v_mov_b32_e32 v44, v47
	v_pk_add_f32 v[44:45], v[50:51], v[44:45]
	v_add_f32_e32 v46, v48, v49
	v_add_f32_e32 v45, v45, v46
	v_add_f32_e32 v44, v44, v45
	v_max_f32_e32 v45, v124, v124
	v_max_f32_e32 v124, v45, v44

.LBB0_1239:
	s_nop 0
	s_and_b64 vcc, exec, s[44:45]
	s_mov_b64 s[8:9], -1
	s_cbranch_vccnz .LBB0_1241
	s_and_b64 s[8:9], s[4:5], exec
	v_readlane_b32 s0, v252, 1
	v_readlane_b32 s1, v252, 5
	v_add_u32_e32 v40, 0xffffc0a0, v148
	s_cselect_b32 s9, s0, s1
	v_readlane_b32 s0, v252, 0
	v_readlane_b32 s1, v252, 2
	s_cselect_b32 s8, s0, s1
	v_ashrrev_i32_e32 v41, 31, v40
	v_ashrrev_i32_e32 v37, 5, v40
	s_movk_i32 s0, 0x480
	v_lshlrev_b64 v[38:39], 13, v[40:41]
	v_mad_i64_i32 v[40:41], s[10:11], v37, s0, v[140:141]
	v_lshl_add_u64 v[38:39], s[8:9], 0, v[38:39]
	s_cselect_b32 s9, s74, s76
	s_cselect_b32 s8, s73, s75
	v_lshlrev_b64 v[40:41], 12, v[40:41]
	v_lshl_add_u64 v[42:43], s[8:9], 0, v[40:41]
	s_cbranch_execz .LBB0_1242
	s_branch .LBB0_1243

.LBB0_1243:
	v_mov_b32_e32 v153, v3
	v_lshl_add_u64 v[40:41], v[38:39], 0, v[2:3]
	v_lshl_add_u64 v[38:39], v[42:43], 0, v[152:153]
	v_mov_b32_e32 v36, v254
	v_pk_mul_f32 v[34:35], v[34:35], v[36:37] op_sel_hi:[1,0]
	v_pk_mul_f32 v[32:33], v[32:33], v[36:37] op_sel_hi:[1,0]
	v_pk_mul_f32 v[30:31], v[30:31], v[36:37] op_sel_hi:[1,0]
	v_pk_mul_f32 v[28:29], v[28:29], v[36:37] op_sel_hi:[1,0]
	s_and_b64 vcc, exec, s[42:43]
	global_store_dwordx4 v[40:41], v[32:35], off
	global_store_dwordx4 v[40:41], v[28:31], off offset:16
	v_cvt_pk_bf16_f32 v42, v32, v33
	v_cvt_pk_bf16_f32 v43, v34, v35
	v_cvt_pk_bf16_f32 v44, v28, v29
	v_cvt_pk_bf16_f32 v45, v30, v31
	global_store_dwordx4 v[38:39], v[42:45], off
	s_cbranch_vccnz .LBB0_1245
	v_pk_mul_f32 v[34:35], v[34:35], v[34:35]
	v_pk_mul_f32 v[32:33], v[32:33], v[32:33]
	v_pk_mul_f32 v[30:31], v[30:31], v[30:31]
	v_pk_mul_f32 v[28:29], v[28:29], v[28:29]
	v_pk_mov_b32 v[42:43], v[32:33], v[34:35] op_sel:[1,0]
	v_mov_b32_e32 v33, v35
	v_pk_add_f32 v[32:33], v[42:43], v[32:33]
	v_mov_b32_e32 v34, v30
	v_mov_b32_e32 v35, v28
	v_mov_b32_e32 v28, v31
	v_pk_add_f32 v[28:29], v[34:35], v[28:29]
	v_add_f32_e32 v30, v32, v33
	v_add_f32_e32 v29, v29, v30
	v_add_f32_e32 v28, v28, v29
	v_max_f32_e32 v29, v124, v124
	v_max_f32_e32 v124, v29, v28

.LBB0_1247:
	s_nop 0
	s_and_b64 vcc, exec, s[44:45]
	s_mov_b64 s[8:9], -1
	s_cbranch_vccnz .LBB0_1249
	s_and_b64 s[8:9], s[4:5], exec
	v_readlane_b32 s0, v252, 1
	v_readlane_b32 s1, v252, 5
	v_add_u32_e32 v24, 0xffffc0b0, v148
	s_cselect_b32 s9, s0, s1
	v_readlane_b32 s0, v252, 0
	v_readlane_b32 s1, v252, 2
	s_cselect_b32 s8, s0, s1
	v_ashrrev_i32_e32 v25, 31, v24
	v_ashrrev_i32_e32 v21, 5, v24
	s_movk_i32 s0, 0x480
	v_lshlrev_b64 v[22:23], 13, v[24:25]
	v_mad_i64_i32 v[24:25], s[10:11], v21, s0, v[142:143]
	v_lshl_add_u64 v[22:23], s[8:9], 0, v[22:23]
	s_cselect_b32 s9, s74, s76
	s_cselect_b32 s8, s73, s75
	v_lshlrev_b64 v[24:25], 12, v[24:25]
	v_lshl_add_u64 v[26:27], s[8:9], 0, v[24:25]
	s_cbranch_execz .LBB0_1250
	s_branch .LBB0_1251

.LBB0_1251:
	v_mov_b32_e32 v153, v3
	v_lshl_add_u64 v[24:25], v[22:23], 0, v[2:3]
	v_lshl_add_u64 v[22:23], v[26:27], 0, v[152:153]
	v_mov_b32_e32 v20, v255
	v_pk_mul_f32 v[18:19], v[18:19], v[20:21] op_sel_hi:[1,0]
	v_pk_mul_f32 v[16:17], v[16:17], v[20:21] op_sel_hi:[1,0]
	v_pk_mul_f32 v[14:15], v[14:15], v[20:21] op_sel_hi:[1,0]
	v_pk_mul_f32 v[12:13], v[12:13], v[20:21] op_sel_hi:[1,0]
	s_and_b64 vcc, exec, s[42:43]
	global_store_dwordx4 v[24:25], v[16:19], off
	global_store_dwordx4 v[24:25], v[12:15], off offset:16
	v_cvt_pk_bf16_f32 v26, v16, v17
	v_cvt_pk_bf16_f32 v27, v18, v19
	v_cvt_pk_bf16_f32 v28, v12, v13
	v_cvt_pk_bf16_f32 v29, v14, v15
	global_store_dwordx4 v[22:23], v[26:29], off
	s_cbranch_vccnz .LBB0_1253
	v_pk_mul_f32 v[18:19], v[18:19], v[18:19]
	v_pk_mul_f32 v[16:17], v[16:17], v[16:17]
	v_pk_mul_f32 v[14:15], v[14:15], v[14:15]
	v_pk_mul_f32 v[12:13], v[12:13], v[12:13]
	v_pk_mov_b32 v[26:27], v[16:17], v[18:19] op_sel:[1,0]
	v_mov_b32_e32 v17, v19
	v_pk_add_f32 v[16:17], v[26:27], v[16:17]
	v_mov_b32_e32 v18, v14
	v_mov_b32_e32 v19, v12
	v_mov_b32_e32 v12, v15
	v_pk_add_f32 v[12:13], v[18:19], v[12:13]
	v_add_f32_e32 v2, v16, v17
	v_add_f32_e32 v2, v13, v2
	v_add_f32_e32 v2, v12, v2
	v_max_f32_e32 v12, v124, v124
	v_max_f32_e32 v124, v12, v2

	.amdhsa_kernel _Z8yoco_fwd6Params
		.amdhsa_group_segment_fixed_size 0
		.amdhsa_private_segment_fixed_size 0
		.amdhsa_kernarg_size 448
		.amdhsa_user_sgpr_count 2
		.amdhsa_user_sgpr_dispatch_ptr 0
		.amdhsa_user_sgpr_queue_ptr 0
		.amdhsa_user_sgpr_kernarg_segment_ptr 1
		.amdhsa_user_sgpr_dispatch_id 0
		.amdhsa_user_sgpr_kernarg_preload_length 0
		.amdhsa_user_sgpr_kernarg_preload_offset 0
		.amdhsa_user_sgpr_private_segment_size 0
		.amdhsa_uses_dynamic_stack 0
		.amdhsa_enable_private_segment 0
		.amdhsa_system_sgpr_workgroup_id_x 1
		.amdhsa_system_sgpr_workgroup_id_y 0
		.amdhsa_system_sgpr_workgroup_id_z 0
		.amdhsa_system_sgpr_workgroup_info 0
		.amdhsa_system_vgpr_workitem_id 0
		.amdhsa_next_free_vgpr 256
		.amdhsa_next_free_sgpr 100
		.amdhsa_accum_offset 256
		.amdhsa_reserve_vcc 1
		.amdhsa_float_round_mode_32 0
		.amdhsa_float_round_mode_16_64 0
		.amdhsa_float_denorm_mode_32 3
		.amdhsa_float_denorm_mode_16_64 3
		.amdhsa_dx10_clamp 1
		.amdhsa_ieee_mode 1
		.amdhsa_fp16_overflow 0
		.amdhsa_tg_split 0
		.amdhsa_exception_fp_ieee_invalid_op 0
		.amdhsa_exception_fp_denorm_src 0
		.amdhsa_exception_fp_ieee_div_zero 0
		.amdhsa_exception_fp_ieee_overflow 0
		.amdhsa_exception_fp_ieee_underflow 0
		.amdhsa_exception_fp_ieee_inexact 0
		.amdhsa_exception_int_div_zero 0
	.end_amdhsa_kernel

amdhsa.kernels:
  - .agpr_count:     0
    .args:
      - .offset:         0
        .size:           192
        .value_kind:     by_value
      - .offset:         192
        .size:           4
        .value_kind:     hidden_block_count_x
      - .offset:         196
        .size:           4
        .value_kind:     hidden_block_count_y
      - .offset:         200
        .size:           4
        .value_kind:     hidden_block_count_z
      - .offset:         204
        .size:           2
        .value_kind:     hidden_group_size_x
      - .offset:         206
        .size:           2
        .value_kind:     hidden_group_size_y
      - .offset:         208
        .size:           2
        .value_kind:     hidden_group_size_z
      - .offset:         210
        .size:           2
        .value_kind:     hidden_remainder_x
      - .offset:         212
        .size:           2
        .value_kind:     hidden_remainder_y
      - .offset:         214
        .size:           2
        .value_kind:     hidden_remainder_z
      - .offset:         232
        .size:           8
        .value_kind:     hidden_global_offset_x
      - .offset:         240
        .size:           8
        .value_kind:     hidden_global_offset_y
      - .offset:         248
        .size:           8
        .value_kind:     hidden_global_offset_z
      - .offset:         256
        .size:           2
        .value_kind:     hidden_grid_dims
      - .offset:         312
        .size:           4
        .value_kind:     hidden_dynamic_lds_size
    .group_segment_fixed_size: 0
    .kernarg_segment_align: 8
    .kernarg_segment_size: 448
    .language:       OpenCL C
    .language_version:
      - 2
      - 0
    .max_flat_workgroup_size: 512
    .name:           _Z8yoco_fwd6Params
    .private_segment_fixed_size: 0
    .sgpr_count:     106
    .sgpr_spill_count: 117
    .symbol:         _Z8yoco_fwd6Params.kd
    .uniform_work_group_size: 1
    .uses_dynamic_stack: false
    .vgpr_count:     256
    .vgpr_spill_count: 0
    .wavefront_size: 64
